# phase2 pool: sample-token jobs moved to blocks>=384 and de-serialised (all window loads issued before one wait); prompt jobs double-buffered
# speedup vs baseline: 1.0053x; 1.0053x over previous
.LBB0_253:
	s_cmp_lt_i32 s92, 3
	s_cselect_b64 s[0:1], -1, 0
	s_cmp_gt_i32 s93, 2
	s_cselect_b64 s[4:5], -1, 0
	s_and_b64 s[0:1], s[0:1], s[4:5]
	s_andn2_b64 vcc, exec, s[0:1]
	s_cbranch_vccnz .LBB0_489
	s_cmpk_gt_i32 s2, 0x107f
	s_cbranch_scc1 .LBB0_271
	v_lshlrev_b32_e32 v2, 3, v218
	v_bfe_u32 v1, v218, 4, 2
	v_and_b32_e32 v2, 0x78, v2
	v_lshl_or_b32 v2, v1, 7, v2
	v_and_b32_e32 v0, 63, v218
	v_lshlrev_b32_e32 v8, 1, v2
	v_mov_b32_e32 v9, 0
	v_lshl_add_u64 v[10:11], s[90:91], 0, v[8:9]
	v_lshlrev_b32_e32 v8, 4, v0
	v_lshl_add_u64 v[12:13], s[88:89], 0, v[8:9]
	v_lshlrev_b32_e32 v8, 2, v2
	v_lshlrev_b32_e64 v38, v1, 2
	v_lshl_add_u64 v[0:1], s[72:73], 0, v[8:9]
	s_mov_b64 s[0:1], 0x7010
	v_lshl_add_u64 v[14:15], v[0:1], 0, s[0:1]
	s_movk_i32 s0, 0xfc00
	s_mov_b32 s1, -1
	v_lshl_add_u64 v[16:17], v[10:11], 0, s[0:1]
	s_movk_i32 s3, 0x1200
	s_mov_b32 s8, s2
	s_cmpk_lg_i32 s94, 0x200
	s_cbranch_scc1 .Lpool_skip
	v_and_b32_e32 v172, 63, v218
	v_lshrrev_b32_e32 v173, 4, v172
	v_and_b32_e32 v174, 15, v172
	v_lshlrev_b32_e32 v175, 4, v172
	v_lshlrev_b32_e32 v174, 3, v174
	v_lshl_add_u32 v172, v173, 7, v174
	v_lshlrev_b32_e32 v172, 1, v172
	v_add_u32_e32 v172, 0xe00, v172
	v_lshlrev_b32_e64 v173, v173, 2
	v_lshrrev_b32_e32 v174, 6, v218
	s_lshl_b32 s21, s2, 2
	s_nop 1
	v_readfirstlane_b32 s20, v174
	s_nop 1
	s_mov_b32 s23, s20
	s_add_i32 s20, s20, s21
	s_mov_b32 s22, s20
	s_add_i32 s21, s20, 1
	v_min_u32_e32 v173, s21, v173
	v_cvt_f32_u32_e32 v0, v173
	v_div_scale_f32 v1, s[0:1], v0, v0, 1.0
	v_rcp_f32_e32 v2, v1
	v_div_scale_f32 v3, vcc, 1.0, v0, 1.0
	v_fma_f32 v4, -v1, v2, 1.0
	v_fmac_f32_e32 v2, v4, v2
	v_mul_f32_e32 v4, v3, v2
	v_fma_f32 v5, -v1, v4, v3
	v_fmac_f32_e32 v4, v5, v2
	v_fma_f32 v1, -v1, v4, v3
	v_div_fmas_f32 v1, v1, v2, v4
	v_div_fixup_f32 v174, v1, v0, 1.0
	s_mov_b32 s21, s20
	s_max_i32 s21, s21, 0
	s_mul_i32 s21, s21, 0x1200
	s_add_u32 s24, s90, s21
	s_addc_u32 s25, s91, 0
	global_load_dwordx4 v[44:47], v172, s[24:25]
	s_sub_i32 s21, s20, 1
	s_max_i32 s21, s21, 0
	s_mul_i32 s21, s21, 0x1200
	s_add_u32 s24, s90, s21
	s_addc_u32 s25, s91, 0
	global_load_dwordx4 v[48:51], v172, s[24:25]
	s_sub_i32 s21, s20, 2
	s_max_i32 s21, s21, 0
	s_mul_i32 s21, s21, 0x1200
	s_add_u32 s24, s90, s21
	s_addc_u32 s25, s91, 0
	global_load_dwordx4 v[52:55], v172, s[24:25]
	s_sub_i32 s21, s20, 3
	s_max_i32 s21, s21, 0
	s_mul_i32 s21, s21, 0x1200
	s_add_u32 s24, s90, s21
	s_addc_u32 s25, s91, 0
	global_load_dwordx4 v[56:59], v172, s[24:25]
	s_sub_i32 s21, s20, 4
	s_max_i32 s21, s21, 0
	s_mul_i32 s21, s21, 0x1200
	s_add_u32 s24, s90, s21
	s_addc_u32 s25, s91, 0
	global_load_dwordx4 v[60:63], v172, s[24:25]
	s_sub_i32 s21, s20, 5
	s_max_i32 s21, s21, 0
	s_mul_i32 s21, s21, 0x1200
	s_add_u32 s24, s90, s21
	s_addc_u32 s25, s91, 0
	global_load_dwordx4 v[64:67], v172, s[24:25]
	s_sub_i32 s21, s20, 6
	s_max_i32 s21, s21, 0
	s_mul_i32 s21, s21, 0x1200
	s_add_u32 s24, s90, s21
	s_addc_u32 s25, s91, 0
	global_load_dwordx4 v[68:71], v172, s[24:25]
	s_sub_i32 s21, s20, 7
	s_max_i32 s21, s21, 0
	s_mul_i32 s21, s21, 0x1200
	s_add_u32 s24, s90, s21
	s_addc_u32 s25, s91, 0
	global_load_dwordx4 v[72:75], v172, s[24:25]
	s_sub_i32 s21, s20, 8
	s_max_i32 s21, s21, 0
	s_mul_i32 s21, s21, 0x1200
	s_add_u32 s24, s90, s21
	s_addc_u32 s25, s91, 0
	global_load_dwordx4 v[76:79], v172, s[24:25]
	s_sub_i32 s21, s20, 9
	s_max_i32 s21, s21, 0
	s_mul_i32 s21, s21, 0x1200
	s_add_u32 s24, s90, s21
	s_addc_u32 s25, s91, 0
	global_load_dwordx4 v[80:83], v172, s[24:25]
	s_sub_i32 s21, s20, 10
	s_max_i32 s21, s21, 0
	s_mul_i32 s21, s21, 0x1200
	s_add_u32 s24, s90, s21
	s_addc_u32 s25, s91, 0
	global_load_dwordx4 v[84:87], v172, s[24:25]
	s_sub_i32 s21, s20, 11
	s_max_i32 s21, s21, 0
	s_mul_i32 s21, s21, 0x1200
	s_add_u32 s24, s90, s21
	s_addc_u32 s25, s91, 0
	global_load_dwordx4 v[88:91], v172, s[24:25]
	s_sub_i32 s21, s20, 12
	s_max_i32 s21, s21, 0
	s_mul_i32 s21, s21, 0x1200
	s_add_u32 s24, s90, s21
	s_addc_u32 s25, s91, 0
	global_load_dwordx4 v[92:95], v172, s[24:25]
	s_sub_i32 s21, s20, 13
	s_max_i32 s21, s21, 0
	s_mul_i32 s21, s21, 0x1200
	s_add_u32 s24, s90, s21
	s_addc_u32 s25, s91, 0
	global_load_dwordx4 v[96:99], v172, s[24:25]
	s_sub_i32 s21, s20, 14
	s_max_i32 s21, s21, 0
	s_mul_i32 s21, s21, 0x1200
	s_add_u32 s24, s90, s21
	s_addc_u32 s25, s91, 0
	global_load_dwordx4 v[100:103], v172, s[24:25]
	s_sub_i32 s21, s20, 15
	s_max_i32 s21, s21, 0
	s_mul_i32 s21, s21, 0x1200
	s_add_u32 s24, s90, s21
	s_addc_u32 s25, s91, 0
	global_load_dwordx4 v[104:107], v172, s[24:25]
	s_add_i32 s20, s20, 0x800
	s_mov_b32 s21, s20
	s_max_i32 s21, s21, 0
	s_mul_i32 s21, s21, 0x1200
	s_add_u32 s24, s90, s21
	s_addc_u32 s25, s91, 0
	global_load_dwordx4 v[108:111], v172, s[24:25]
	s_sub_i32 s21, s20, 1
	s_max_i32 s21, s21, 0
	s_mul_i32 s21, s21, 0x1200
	s_add_u32 s24, s90, s21
	s_addc_u32 s25, s91, 0
	global_load_dwordx4 v[112:115], v172, s[24:25]
	s_sub_i32 s21, s20, 2
	s_max_i32 s21, s21, 0
	s_mul_i32 s21, s21, 0x1200
	s_add_u32 s24, s90, s21
	s_addc_u32 s25, s91, 0
	global_load_dwordx4 v[116:119], v172, s[24:25]
	s_sub_i32 s21, s20, 3
	s_max_i32 s21, s21, 0
	s_mul_i32 s21, s21, 0x1200
	s_add_u32 s24, s90, s21
	s_addc_u32 s25, s91, 0
	global_load_dwordx4 v[120:123], v172, s[24:25]
	s_sub_i32 s21, s20, 4
	s_max_i32 s21, s21, 0
	s_mul_i32 s21, s21, 0x1200
	s_add_u32 s24, s90, s21
	s_addc_u32 s25, s91, 0
	global_load_dwordx4 v[124:127], v172, s[24:25]
	s_sub_i32 s21, s20, 5
	s_max_i32 s21, s21, 0
	s_mul_i32 s21, s21, 0x1200
	s_add_u32 s24, s90, s21
	s_addc_u32 s25, s91, 0
	global_load_dwordx4 v[128:131], v172, s[24:25]
	s_sub_i32 s21, s20, 6
	s_max_i32 s21, s21, 0
	s_mul_i32 s21, s21, 0x1200
	s_add_u32 s24, s90, s21
	s_addc_u32 s25, s91, 0
	global_load_dwordx4 v[132:135], v172, s[24:25]
	s_sub_i32 s21, s20, 7
	s_max_i32 s21, s21, 0
	s_mul_i32 s21, s21, 0x1200
	s_add_u32 s24, s90, s21
	s_addc_u32 s25, s91, 0
	global_load_dwordx4 v[136:139], v172, s[24:25]
	s_sub_i32 s21, s20, 8
	s_max_i32 s21, s21, 0
	s_mul_i32 s21, s21, 0x1200
	s_add_u32 s24, s90, s21
	s_addc_u32 s25, s91, 0
	global_load_dwordx4 v[140:143], v172, s[24:25]
	s_sub_i32 s21, s20, 9
	s_max_i32 s21, s21, 0
	s_mul_i32 s21, s21, 0x1200
	s_add_u32 s24, s90, s21
	s_addc_u32 s25, s91, 0
	global_load_dwordx4 v[144:147], v172, s[24:25]
	s_sub_i32 s21, s20, 10
	s_max_i32 s21, s21, 0
	s_mul_i32 s21, s21, 0x1200
	s_add_u32 s24, s90, s21
	s_addc_u32 s25, s91, 0
	global_load_dwordx4 v[148:151], v172, s[24:25]
	s_sub_i32 s21, s20, 11
	s_max_i32 s21, s21, 0
	s_mul_i32 s21, s21, 0x1200
	s_add_u32 s24, s90, s21
	s_addc_u32 s25, s91, 0
	global_load_dwordx4 v[152:155], v172, s[24:25]
	s_sub_i32 s21, s20, 12
	s_max_i32 s21, s21, 0
	s_mul_i32 s21, s21, 0x1200
	s_add_u32 s24, s90, s21
	s_addc_u32 s25, s91, 0
	global_load_dwordx4 v[156:159], v172, s[24:25]
	s_sub_i32 s21, s20, 13
	s_max_i32 s21, s21, 0
	s_mul_i32 s21, s21, 0x1200
	s_add_u32 s24, s90, s21
	s_addc_u32 s25, s91, 0
	global_load_dwordx4 v[160:163], v172, s[24:25]
	s_sub_i32 s21, s20, 14
	s_max_i32 s21, s21, 0
	s_mul_i32 s21, s21, 0x1200
	s_add_u32 s24, s90, s21
	s_addc_u32 s25, s91, 0
	global_load_dwordx4 v[164:167], v172, s[24:25]
	s_sub_i32 s21, s20, 15
	s_max_i32 s21, s21, 0
	s_mul_i32 s21, s21, 0x1200
	s_add_u32 s24, s90, s21
	s_addc_u32 s25, s91, 0
	global_load_dwordx4 v[168:171], v172, s[24:25]
	s_waitcnt vmcnt(16)
	v_lshlrev_b32_e32 v182, 16, v44
	v_and_b32_e32 v183, 0xffff0000, v44
	v_lshlrev_b32_e32 v180, 16, v45
	v_and_b32_e32 v181, 0xffff0000, v45
	v_lshlrev_b32_e32 v178, 16, v46
	v_and_b32_e32 v179, 0xffff0000, v46
	v_lshlrev_b32_e32 v176, 16, v47
	v_and_b32_e32 v177, 0xffff0000, v47
	v_mov_b32_e32 v184, v176
	v_mov_b32_e32 v185, v177
	v_mov_b32_e32 v186, v178
	v_mov_b32_e32 v187, v179
	v_mov_b32_e32 v188, v180
	v_mov_b32_e32 v189, v181
	v_mov_b32_e32 v190, v182
	v_mov_b32_e32 v191, v183
	s_mov_b64 s[26:27], exec
	v_cmp_lt_u32_e32 vcc, 1, v173
	s_and_b64 exec, exec, vcc
	v_lshlrev_b32_e32 v198, 16, v48
	v_and_b32_e32 v199, 0xffff0000, v48
	v_lshlrev_b32_e32 v196, 16, v49
	v_and_b32_e32 v197, 0xffff0000, v49
	v_lshlrev_b32_e32 v194, 16, v50
	v_and_b32_e32 v195, 0xffff0000, v50
	v_lshlrev_b32_e32 v192, 16, v51
	v_and_b32_e32 v193, 0xffff0000, v51
	v_pk_add_f32 v[184:185], v[184:185], v[192:193]
	v_pk_add_f32 v[186:187], v[186:187], v[194:195]
	v_pk_add_f32 v[188:189], v[188:189], v[196:197]
	v_pk_add_f32 v[190:191], v[190:191], v[198:199]
	v_cmp_lt_u32_e32 vcc, 2, v173
	s_and_b64 exec, exec, vcc
	v_lshlrev_b32_e32 v198, 16, v52
	v_and_b32_e32 v199, 0xffff0000, v52
	v_lshlrev_b32_e32 v196, 16, v53
	v_and_b32_e32 v197, 0xffff0000, v53
	v_lshlrev_b32_e32 v194, 16, v54
	v_and_b32_e32 v195, 0xffff0000, v54
	v_lshlrev_b32_e32 v192, 16, v55
	v_and_b32_e32 v193, 0xffff0000, v55
	v_pk_add_f32 v[184:185], v[184:185], v[192:193]
	v_pk_add_f32 v[186:187], v[186:187], v[194:195]
	v_pk_add_f32 v[188:189], v[188:189], v[196:197]
	v_pk_add_f32 v[190:191], v[190:191], v[198:199]
	v_cmp_lt_u32_e32 vcc, 3, v173
	s_and_b64 exec, exec, vcc
	v_lshlrev_b32_e32 v198, 16, v56
	v_and_b32_e32 v199, 0xffff0000, v56
	v_lshlrev_b32_e32 v196, 16, v57
	v_and_b32_e32 v197, 0xffff0000, v57
	v_lshlrev_b32_e32 v194, 16, v58
	v_and_b32_e32 v195, 0xffff0000, v58
	v_lshlrev_b32_e32 v192, 16, v59
	v_and_b32_e32 v193, 0xffff0000, v59
	v_pk_add_f32 v[184:185], v[184:185], v[192:193]
	v_pk_add_f32 v[186:187], v[186:187], v[194:195]
	v_pk_add_f32 v[188:189], v[188:189], v[196:197]
	v_pk_add_f32 v[190:191], v[190:191], v[198:199]
	v_cmp_lt_u32_e32 vcc, 4, v173
	s_and_b64 exec, exec, vcc
	v_lshlrev_b32_e32 v198, 16, v60
	v_and_b32_e32 v199, 0xffff0000, v60
	v_lshlrev_b32_e32 v196, 16, v61
	v_and_b32_e32 v197, 0xffff0000, v61
	v_lshlrev_b32_e32 v194, 16, v62
	v_and_b32_e32 v195, 0xffff0000, v62
	v_lshlrev_b32_e32 v192, 16, v63
	v_and_b32_e32 v193, 0xffff0000, v63
	v_pk_add_f32 v[184:185], v[184:185], v[192:193]
	v_pk_add_f32 v[186:187], v[186:187], v[194:195]
	v_pk_add_f32 v[188:189], v[188:189], v[196:197]
	v_pk_add_f32 v[190:191], v[190:191], v[198:199]
	v_cmp_lt_u32_e32 vcc, 5, v173
	s_and_b64 exec, exec, vcc
	v_lshlrev_b32_e32 v198, 16, v64
	v_and_b32_e32 v199, 0xffff0000, v64
	v_lshlrev_b32_e32 v196, 16, v65
	v_and_b32_e32 v197, 0xffff0000, v65
	v_lshlrev_b32_e32 v194, 16, v66
	v_and_b32_e32 v195, 0xffff0000, v66
	v_lshlrev_b32_e32 v192, 16, v67
	v_and_b32_e32 v193, 0xffff0000, v67
	v_pk_add_f32 v[184:185], v[184:185], v[192:193]
	v_pk_add_f32 v[186:187], v[186:187], v[194:195]
	v_pk_add_f32 v[188:189], v[188:189], v[196:197]
	v_pk_add_f32 v[190:191], v[190:191], v[198:199]
	v_cmp_lt_u32_e32 vcc, 6, v173
	s_and_b64 exec, exec, vcc
	v_lshlrev_b32_e32 v198, 16, v68
	v_and_b32_e32 v199, 0xffff0000, v68
	v_lshlrev_b32_e32 v196, 16, v69
	v_and_b32_e32 v197, 0xffff0000, v69
	v_lshlrev_b32_e32 v194, 16, v70
	v_and_b32_e32 v195, 0xffff0000, v70
	v_lshlrev_b32_e32 v192, 16, v71
	v_and_b32_e32 v193, 0xffff0000, v71
	v_pk_add_f32 v[184:185], v[184:185], v[192:193]
	v_pk_add_f32 v[186:187], v[186:187], v[194:195]
	v_pk_add_f32 v[188:189], v[188:189], v[196:197]
	v_pk_add_f32 v[190:191], v[190:191], v[198:199]
	v_cmp_lt_u32_e32 vcc, 7, v173
	s_and_b64 exec, exec, vcc
	v_lshlrev_b32_e32 v198, 16, v72
	v_and_b32_e32 v199, 0xffff0000, v72
	v_lshlrev_b32_e32 v196, 16, v73
	v_and_b32_e32 v197, 0xffff0000, v73
	v_lshlrev_b32_e32 v194, 16, v74
	v_and_b32_e32 v195, 0xffff0000, v74
	v_lshlrev_b32_e32 v192, 16, v75
	v_and_b32_e32 v193, 0xffff0000, v75
	v_pk_add_f32 v[184:185], v[184:185], v[192:193]
	v_pk_add_f32 v[186:187], v[186:187], v[194:195]
	v_pk_add_f32 v[188:189], v[188:189], v[196:197]
	v_pk_add_f32 v[190:191], v[190:191], v[198:199]
	v_cmp_lt_u32_e32 vcc, 8, v173
	s_and_b64 exec, exec, vcc
	v_lshlrev_b32_e32 v198, 16, v76
	v_and_b32_e32 v199, 0xffff0000, v76
	v_lshlrev_b32_e32 v196, 16, v77
	v_and_b32_e32 v197, 0xffff0000, v77
	v_lshlrev_b32_e32 v194, 16, v78
	v_and_b32_e32 v195, 0xffff0000, v78
	v_lshlrev_b32_e32 v192, 16, v79
	v_and_b32_e32 v193, 0xffff0000, v79
	v_pk_add_f32 v[184:185], v[184:185], v[192:193]
	v_pk_add_f32 v[186:187], v[186:187], v[194:195]
	v_pk_add_f32 v[188:189], v[188:189], v[196:197]
	v_pk_add_f32 v[190:191], v[190:191], v[198:199]
	v_cmp_lt_u32_e32 vcc, 9, v173
	s_and_b64 exec, exec, vcc
	v_lshlrev_b32_e32 v198, 16, v80
	v_and_b32_e32 v199, 0xffff0000, v80
	v_lshlrev_b32_e32 v196, 16, v81
	v_and_b32_e32 v197, 0xffff0000, v81
	v_lshlrev_b32_e32 v194, 16, v82
	v_and_b32_e32 v195, 0xffff0000, v82
	v_lshlrev_b32_e32 v192, 16, v83
	v_and_b32_e32 v193, 0xffff0000, v83
	v_pk_add_f32 v[184:185], v[184:185], v[192:193]
	v_pk_add_f32 v[186:187], v[186:187], v[194:195]
	v_pk_add_f32 v[188:189], v[188:189], v[196:197]
	v_pk_add_f32 v[190:191], v[190:191], v[198:199]
	v_cmp_lt_u32_e32 vcc, 10, v173
	s_and_b64 exec, exec, vcc
	v_lshlrev_b32_e32 v198, 16, v84
	v_and_b32_e32 v199, 0xffff0000, v84
	v_lshlrev_b32_e32 v196, 16, v85
	v_and_b32_e32 v197, 0xffff0000, v85
	v_lshlrev_b32_e32 v194, 16, v86
	v_and_b32_e32 v195, 0xffff0000, v86
	v_lshlrev_b32_e32 v192, 16, v87
	v_and_b32_e32 v193, 0xffff0000, v87
	v_pk_add_f32 v[184:185], v[184:185], v[192:193]
	v_pk_add_f32 v[186:187], v[186:187], v[194:195]
	v_pk_add_f32 v[188:189], v[188:189], v[196:197]
	v_pk_add_f32 v[190:191], v[190:191], v[198:199]
	v_cmp_lt_u32_e32 vcc, 11, v173
	s_and_b64 exec, exec, vcc
	v_lshlrev_b32_e32 v198, 16, v88
	v_and_b32_e32 v199, 0xffff0000, v88
	v_lshlrev_b32_e32 v196, 16, v89
	v_and_b32_e32 v197, 0xffff0000, v89
	v_lshlrev_b32_e32 v194, 16, v90
	v_and_b32_e32 v195, 0xffff0000, v90
	v_lshlrev_b32_e32 v192, 16, v91
	v_and_b32_e32 v193, 0xffff0000, v91
	v_pk_add_f32 v[184:185], v[184:185], v[192:193]
	v_pk_add_f32 v[186:187], v[186:187], v[194:195]
	v_pk_add_f32 v[188:189], v[188:189], v[196:197]
	v_pk_add_f32 v[190:191], v[190:191], v[198:199]
	v_cmp_lt_u32_e32 vcc, 12, v173
	s_and_b64 exec, exec, vcc
	v_lshlrev_b32_e32 v198, 16, v92
	v_and_b32_e32 v199, 0xffff0000, v92
	v_lshlrev_b32_e32 v196, 16, v93
	v_and_b32_e32 v197, 0xffff0000, v93
	v_lshlrev_b32_e32 v194, 16, v94
	v_and_b32_e32 v195, 0xffff0000, v94
	v_lshlrev_b32_e32 v192, 16, v95
	v_and_b32_e32 v193, 0xffff0000, v95
	v_pk_add_f32 v[184:185], v[184:185], v[192:193]
	v_pk_add_f32 v[186:187], v[186:187], v[194:195]
	v_pk_add_f32 v[188:189], v[188:189], v[196:197]
	v_pk_add_f32 v[190:191], v[190:191], v[198:199]
	v_cmp_lt_u32_e32 vcc, 13, v173
	s_and_b64 exec, exec, vcc
	v_lshlrev_b32_e32 v198, 16, v96
	v_and_b32_e32 v199, 0xffff0000, v96
	v_lshlrev_b32_e32 v196, 16, v97
	v_and_b32_e32 v197, 0xffff0000, v97
	v_lshlrev_b32_e32 v194, 16, v98
	v_and_b32_e32 v195, 0xffff0000, v98
	v_lshlrev_b32_e32 v192, 16, v99
	v_and_b32_e32 v193, 0xffff0000, v99
	v_pk_add_f32 v[184:185], v[184:185], v[192:193]
	v_pk_add_f32 v[186:187], v[186:187], v[194:195]
	v_pk_add_f32 v[188:189], v[188:189], v[196:197]
	v_pk_add_f32 v[190:191], v[190:191], v[198:199]
	v_cmp_lt_u32_e32 vcc, 14, v173
	s_and_b64 exec, exec, vcc
	v_lshlrev_b32_e32 v198, 16, v100
	v_and_b32_e32 v199, 0xffff0000, v100
	v_lshlrev_b32_e32 v196, 16, v101
	v_and_b32_e32 v197, 0xffff0000, v101
	v_lshlrev_b32_e32 v194, 16, v102
	v_and_b32_e32 v195, 0xffff0000, v102
	v_lshlrev_b32_e32 v192, 16, v103
	v_and_b32_e32 v193, 0xffff0000, v103
	v_pk_add_f32 v[184:185], v[184:185], v[192:193]
	v_pk_add_f32 v[186:187], v[186:187], v[194:195]
	v_pk_add_f32 v[188:189], v[188:189], v[196:197]
	v_pk_add_f32 v[190:191], v[190:191], v[198:199]
	v_cmp_lt_u32_e32 vcc, 15, v173
	s_and_b64 exec, exec, vcc
	v_lshlrev_b32_e32 v198, 16, v104
	v_and_b32_e32 v199, 0xffff0000, v104
	v_lshlrev_b32_e32 v196, 16, v105
	v_and_b32_e32 v197, 0xffff0000, v105
	v_lshlrev_b32_e32 v194, 16, v106
	v_and_b32_e32 v195, 0xffff0000, v106
	v_lshlrev_b32_e32 v192, 16, v107
	v_and_b32_e32 v193, 0xffff0000, v107
	v_pk_add_f32 v[184:185], v[184:185], v[192:193]
	v_pk_add_f32 v[186:187], v[186:187], v[194:195]
	v_pk_add_f32 v[188:189], v[188:189], v[196:197]
	v_pk_add_f32 v[190:191], v[190:191], v[198:199]
	s_mov_b64 exec, s[26:27]
	v_pk_fma_f32 v[184:185], v[184:185], v[174:175], v[176:177] op_sel_hi:[1,0,1] neg_lo:[0,0,1] neg_hi:[0,0,1]
	v_pk_fma_f32 v[186:187], v[186:187], v[174:175], v[178:179] op_sel_hi:[1,0,1] neg_lo:[0,0,1] neg_hi:[0,0,1]
	v_pk_fma_f32 v[188:189], v[188:189], v[174:175], v[180:181] op_sel_hi:[1,0,1] neg_lo:[0,0,1] neg_hi:[0,0,1]
	v_pk_fma_f32 v[190:191], v[190:191], v[174:175], v[182:183] op_sel_hi:[1,0,1] neg_lo:[0,0,1] neg_hi:[0,0,1]
	v_cvt_pk_bf16_f32 v200, v190, v191
	v_cvt_pk_bf16_f32 v201, v188, v189
	v_cvt_pk_bf16_f32 v202, v186, v187
	v_cvt_pk_bf16_f32 v203, v184, v185
	s_lshl_b32 s21, s22, 10
	s_add_u32 s24, s88, s21
	s_addc_u32 s25, s89, 0
	global_store_dwordx4 v175, v[200:203], s[24:25]
	s_add_i32 s22, s22, 0x800
	s_add_i32 s20, s20, 0x800
	s_mov_b32 s21, s20
	s_max_i32 s21, s21, 0
	s_mul_i32 s21, s21, 0x1200
	s_add_u32 s24, s90, s21
	s_addc_u32 s25, s91, 0
	global_load_dwordx4 v[44:47], v172, s[24:25]
	s_sub_i32 s21, s20, 1
	s_max_i32 s21, s21, 0
	s_mul_i32 s21, s21, 0x1200
	s_add_u32 s24, s90, s21
	s_addc_u32 s25, s91, 0
	global_load_dwordx4 v[48:51], v172, s[24:25]
	s_sub_i32 s21, s20, 2
	s_max_i32 s21, s21, 0
	s_mul_i32 s21, s21, 0x1200
	s_add_u32 s24, s90, s21
	s_addc_u32 s25, s91, 0
	global_load_dwordx4 v[52:55], v172, s[24:25]
	s_sub_i32 s21, s20, 3
	s_max_i32 s21, s21, 0
	s_mul_i32 s21, s21, 0x1200
	s_add_u32 s24, s90, s21
	s_addc_u32 s25, s91, 0
	global_load_dwordx4 v[56:59], v172, s[24:25]
	s_sub_i32 s21, s20, 4
	s_max_i32 s21, s21, 0
	s_mul_i32 s21, s21, 0x1200
	s_add_u32 s24, s90, s21
	s_addc_u32 s25, s91, 0
	global_load_dwordx4 v[60:63], v172, s[24:25]
	s_sub_i32 s21, s20, 5
	s_max_i32 s21, s21, 0
	s_mul_i32 s21, s21, 0x1200
	s_add_u32 s24, s90, s21
	s_addc_u32 s25, s91, 0
	global_load_dwordx4 v[64:67], v172, s[24:25]
	s_sub_i32 s21, s20, 6
	s_max_i32 s21, s21, 0
	s_mul_i32 s21, s21, 0x1200
	s_add_u32 s24, s90, s21
	s_addc_u32 s25, s91, 0
	global_load_dwordx4 v[68:71], v172, s[24:25]
	s_sub_i32 s21, s20, 7
	s_max_i32 s21, s21, 0
	s_mul_i32 s21, s21, 0x1200
	s_add_u32 s24, s90, s21
	s_addc_u32 s25, s91, 0
	global_load_dwordx4 v[72:75], v172, s[24:25]
	s_sub_i32 s21, s20, 8
	s_max_i32 s21, s21, 0
	s_mul_i32 s21, s21, 0x1200
	s_add_u32 s24, s90, s21
	s_addc_u32 s25, s91, 0
	global_load_dwordx4 v[76:79], v172, s[24:25]
	s_sub_i32 s21, s20, 9
	s_max_i32 s21, s21, 0
	s_mul_i32 s21, s21, 0x1200
	s_add_u32 s24, s90, s21
	s_addc_u32 s25, s91, 0
	global_load_dwordx4 v[80:83], v172, s[24:25]
	s_sub_i32 s21, s20, 10
	s_max_i32 s21, s21, 0
	s_mul_i32 s21, s21, 0x1200
	s_add_u32 s24, s90, s21
	s_addc_u32 s25, s91, 0
	global_load_dwordx4 v[84:87], v172, s[24:25]
	s_sub_i32 s21, s20, 11
	s_max_i32 s21, s21, 0
	s_mul_i32 s21, s21, 0x1200
	s_add_u32 s24, s90, s21
	s_addc_u32 s25, s91, 0
	global_load_dwordx4 v[88:91], v172, s[24:25]
	s_sub_i32 s21, s20, 12
	s_max_i32 s21, s21, 0
	s_mul_i32 s21, s21, 0x1200
	s_add_u32 s24, s90, s21
	s_addc_u32 s25, s91, 0
	global_load_dwordx4 v[92:95], v172, s[24:25]
	s_sub_i32 s21, s20, 13
	s_max_i32 s21, s21, 0
	s_mul_i32 s21, s21, 0x1200
	s_add_u32 s24, s90, s21
	s_addc_u32 s25, s91, 0
	global_load_dwordx4 v[96:99], v172, s[24:25]
	s_sub_i32 s21, s20, 14
	s_max_i32 s21, s21, 0
	s_mul_i32 s21, s21, 0x1200
	s_add_u32 s24, s90, s21
	s_addc_u32 s25, s91, 0
	global_load_dwordx4 v[100:103], v172, s[24:25]
	s_sub_i32 s21, s20, 15
	s_max_i32 s21, s21, 0
	s_mul_i32 s21, s21, 0x1200
	s_add_u32 s24, s90, s21
	s_addc_u32 s25, s91, 0
	global_load_dwordx4 v[104:107], v172, s[24:25]
	s_waitcnt vmcnt(17)
	v_lshlrev_b32_e32 v182, 16, v108
	v_and_b32_e32 v183, 0xffff0000, v108
	v_lshlrev_b32_e32 v180, 16, v109
	v_and_b32_e32 v181, 0xffff0000, v109
	v_lshlrev_b32_e32 v178, 16, v110
	v_and_b32_e32 v179, 0xffff0000, v110
	v_lshlrev_b32_e32 v176, 16, v111
	v_and_b32_e32 v177, 0xffff0000, v111
	v_mov_b32_e32 v184, v176
	v_mov_b32_e32 v185, v177
	v_mov_b32_e32 v186, v178
	v_mov_b32_e32 v187, v179
	v_mov_b32_e32 v188, v180
	v_mov_b32_e32 v189, v181
	v_mov_b32_e32 v190, v182
	v_mov_b32_e32 v191, v183
	s_mov_b64 s[26:27], exec
	v_cmp_lt_u32_e32 vcc, 1, v173
	s_and_b64 exec, exec, vcc
	v_lshlrev_b32_e32 v198, 16, v112
	v_and_b32_e32 v199, 0xffff0000, v112
	v_lshlrev_b32_e32 v196, 16, v113
	v_and_b32_e32 v197, 0xffff0000, v113
	v_lshlrev_b32_e32 v194, 16, v114
	v_and_b32_e32 v195, 0xffff0000, v114
	v_lshlrev_b32_e32 v192, 16, v115
	v_and_b32_e32 v193, 0xffff0000, v115
	v_pk_add_f32 v[184:185], v[184:185], v[192:193]
	v_pk_add_f32 v[186:187], v[186:187], v[194:195]
	v_pk_add_f32 v[188:189], v[188:189], v[196:197]
	v_pk_add_f32 v[190:191], v[190:191], v[198:199]
	v_cmp_lt_u32_e32 vcc, 2, v173
	s_and_b64 exec, exec, vcc
	v_lshlrev_b32_e32 v198, 16, v116
	v_and_b32_e32 v199, 0xffff0000, v116
	v_lshlrev_b32_e32 v196, 16, v117
	v_and_b32_e32 v197, 0xffff0000, v117
	v_lshlrev_b32_e32 v194, 16, v118
	v_and_b32_e32 v195, 0xffff0000, v118
	v_lshlrev_b32_e32 v192, 16, v119
	v_and_b32_e32 v193, 0xffff0000, v119
	v_pk_add_f32 v[184:185], v[184:185], v[192:193]
	v_pk_add_f32 v[186:187], v[186:187], v[194:195]
	v_pk_add_f32 v[188:189], v[188:189], v[196:197]
	v_pk_add_f32 v[190:191], v[190:191], v[198:199]
	v_cmp_lt_u32_e32 vcc, 3, v173
	s_and_b64 exec, exec, vcc
	v_lshlrev_b32_e32 v198, 16, v120
	v_and_b32_e32 v199, 0xffff0000, v120
	v_lshlrev_b32_e32 v196, 16, v121
	v_and_b32_e32 v197, 0xffff0000, v121
	v_lshlrev_b32_e32 v194, 16, v122
	v_and_b32_e32 v195, 0xffff0000, v122
	v_lshlrev_b32_e32 v192, 16, v123
	v_and_b32_e32 v193, 0xffff0000, v123
	v_pk_add_f32 v[184:185], v[184:185], v[192:193]
	v_pk_add_f32 v[186:187], v[186:187], v[194:195]
	v_pk_add_f32 v[188:189], v[188:189], v[196:197]
	v_pk_add_f32 v[190:191], v[190:191], v[198:199]
	v_cmp_lt_u32_e32 vcc, 4, v173
	s_and_b64 exec, exec, vcc
	v_lshlrev_b32_e32 v198, 16, v124
	v_and_b32_e32 v199, 0xffff0000, v124
	v_lshlrev_b32_e32 v196, 16, v125
	v_and_b32_e32 v197, 0xffff0000, v125
	v_lshlrev_b32_e32 v194, 16, v126
	v_and_b32_e32 v195, 0xffff0000, v126
	v_lshlrev_b32_e32 v192, 16, v127
	v_and_b32_e32 v193, 0xffff0000, v127
	v_pk_add_f32 v[184:185], v[184:185], v[192:193]
	v_pk_add_f32 v[186:187], v[186:187], v[194:195]
	v_pk_add_f32 v[188:189], v[188:189], v[196:197]
	v_pk_add_f32 v[190:191], v[190:191], v[198:199]
	v_cmp_lt_u32_e32 vcc, 5, v173
	s_and_b64 exec, exec, vcc
	v_lshlrev_b32_e32 v198, 16, v128
	v_and_b32_e32 v199, 0xffff0000, v128
	v_lshlrev_b32_e32 v196, 16, v129
	v_and_b32_e32 v197, 0xffff0000, v129
	v_lshlrev_b32_e32 v194, 16, v130
	v_and_b32_e32 v195, 0xffff0000, v130
	v_lshlrev_b32_e32 v192, 16, v131
	v_and_b32_e32 v193, 0xffff0000, v131
	v_pk_add_f32 v[184:185], v[184:185], v[192:193]
	v_pk_add_f32 v[186:187], v[186:187], v[194:195]
	v_pk_add_f32 v[188:189], v[188:189], v[196:197]
	v_pk_add_f32 v[190:191], v[190:191], v[198:199]
	v_cmp_lt_u32_e32 vcc, 6, v173
	s_and_b64 exec, exec, vcc
	v_lshlrev_b32_e32 v198, 16, v132
	v_and_b32_e32 v199, 0xffff0000, v132
	v_lshlrev_b32_e32 v196, 16, v133
	v_and_b32_e32 v197, 0xffff0000, v133
	v_lshlrev_b32_e32 v194, 16, v134
	v_and_b32_e32 v195, 0xffff0000, v134
	v_lshlrev_b32_e32 v192, 16, v135
	v_and_b32_e32 v193, 0xffff0000, v135
	v_pk_add_f32 v[184:185], v[184:185], v[192:193]
	v_pk_add_f32 v[186:187], v[186:187], v[194:195]
	v_pk_add_f32 v[188:189], v[188:189], v[196:197]
	v_pk_add_f32 v[190:191], v[190:191], v[198:199]
	v_cmp_lt_u32_e32 vcc, 7, v173
	s_and_b64 exec, exec, vcc
	v_lshlrev_b32_e32 v198, 16, v136
	v_and_b32_e32 v199, 0xffff0000, v136
	v_lshlrev_b32_e32 v196, 16, v137
	v_and_b32_e32 v197, 0xffff0000, v137
	v_lshlrev_b32_e32 v194, 16, v138
	v_and_b32_e32 v195, 0xffff0000, v138
	v_lshlrev_b32_e32 v192, 16, v139
	v_and_b32_e32 v193, 0xffff0000, v139
	v_pk_add_f32 v[184:185], v[184:185], v[192:193]
	v_pk_add_f32 v[186:187], v[186:187], v[194:195]
	v_pk_add_f32 v[188:189], v[188:189], v[196:197]
	v_pk_add_f32 v[190:191], v[190:191], v[198:199]
	v_cmp_lt_u32_e32 vcc, 8, v173
	s_and_b64 exec, exec, vcc
	v_lshlrev_b32_e32 v198, 16, v140
	v_and_b32_e32 v199, 0xffff0000, v140
	v_lshlrev_b32_e32 v196, 16, v141
	v_and_b32_e32 v197, 0xffff0000, v141
	v_lshlrev_b32_e32 v194, 16, v142
	v_and_b32_e32 v195, 0xffff0000, v142
	v_lshlrev_b32_e32 v192, 16, v143
	v_and_b32_e32 v193, 0xffff0000, v143
	v_pk_add_f32 v[184:185], v[184:185], v[192:193]
	v_pk_add_f32 v[186:187], v[186:187], v[194:195]
	v_pk_add_f32 v[188:189], v[188:189], v[196:197]
	v_pk_add_f32 v[190:191], v[190:191], v[198:199]
	v_cmp_lt_u32_e32 vcc, 9, v173
	s_and_b64 exec, exec, vcc
	v_lshlrev_b32_e32 v198, 16, v144
	v_and_b32_e32 v199, 0xffff0000, v144
	v_lshlrev_b32_e32 v196, 16, v145
	v_and_b32_e32 v197, 0xffff0000, v145
	v_lshlrev_b32_e32 v194, 16, v146
	v_and_b32_e32 v195, 0xffff0000, v146
	v_lshlrev_b32_e32 v192, 16, v147
	v_and_b32_e32 v193, 0xffff0000, v147
	v_pk_add_f32 v[184:185], v[184:185], v[192:193]
	v_pk_add_f32 v[186:187], v[186:187], v[194:195]
	v_pk_add_f32 v[188:189], v[188:189], v[196:197]
	v_pk_add_f32 v[190:191], v[190:191], v[198:199]
	v_cmp_lt_u32_e32 vcc, 10, v173
	s_and_b64 exec, exec, vcc
	v_lshlrev_b32_e32 v198, 16, v148
	v_and_b32_e32 v199, 0xffff0000, v148
	v_lshlrev_b32_e32 v196, 16, v149
	v_and_b32_e32 v197, 0xffff0000, v149
	v_lshlrev_b32_e32 v194, 16, v150
	v_and_b32_e32 v195, 0xffff0000, v150
	v_lshlrev_b32_e32 v192, 16, v151
	v_and_b32_e32 v193, 0xffff0000, v151
	v_pk_add_f32 v[184:185], v[184:185], v[192:193]
	v_pk_add_f32 v[186:187], v[186:187], v[194:195]
	v_pk_add_f32 v[188:189], v[188:189], v[196:197]
	v_pk_add_f32 v[190:191], v[190:191], v[198:199]
	v_cmp_lt_u32_e32 vcc, 11, v173
	s_and_b64 exec, exec, vcc
	v_lshlrev_b32_e32 v198, 16, v152
	v_and_b32_e32 v199, 0xffff0000, v152
	v_lshlrev_b32_e32 v196, 16, v153
	v_and_b32_e32 v197, 0xffff0000, v153
	v_lshlrev_b32_e32 v194, 16, v154
	v_and_b32_e32 v195, 0xffff0000, v154
	v_lshlrev_b32_e32 v192, 16, v155
	v_and_b32_e32 v193, 0xffff0000, v155
	v_pk_add_f32 v[184:185], v[184:185], v[192:193]
	v_pk_add_f32 v[186:187], v[186:187], v[194:195]
	v_pk_add_f32 v[188:189], v[188:189], v[196:197]
	v_pk_add_f32 v[190:191], v[190:191], v[198:199]
	v_cmp_lt_u32_e32 vcc, 12, v173
	s_and_b64 exec, exec, vcc
	v_lshlrev_b32_e32 v198, 16, v156
	v_and_b32_e32 v199, 0xffff0000, v156
	v_lshlrev_b32_e32 v196, 16, v157
	v_and_b32_e32 v197, 0xffff0000, v157
	v_lshlrev_b32_e32 v194, 16, v158
	v_and_b32_e32 v195, 0xffff0000, v158
	v_lshlrev_b32_e32 v192, 16, v159
	v_and_b32_e32 v193, 0xffff0000, v159
	v_pk_add_f32 v[184:185], v[184:185], v[192:193]
	v_pk_add_f32 v[186:187], v[186:187], v[194:195]
	v_pk_add_f32 v[188:189], v[188:189], v[196:197]
	v_pk_add_f32 v[190:191], v[190:191], v[198:199]
	v_cmp_lt_u32_e32 vcc, 13, v173
	s_and_b64 exec, exec, vcc
	v_lshlrev_b32_e32 v198, 16, v160
	v_and_b32_e32 v199, 0xffff0000, v160
	v_lshlrev_b32_e32 v196, 16, v161
	v_and_b32_e32 v197, 0xffff0000, v161
	v_lshlrev_b32_e32 v194, 16, v162
	v_and_b32_e32 v195, 0xffff0000, v162
	v_lshlrev_b32_e32 v192, 16, v163
	v_and_b32_e32 v193, 0xffff0000, v163
	v_pk_add_f32 v[184:185], v[184:185], v[192:193]
	v_pk_add_f32 v[186:187], v[186:187], v[194:195]
	v_pk_add_f32 v[188:189], v[188:189], v[196:197]
	v_pk_add_f32 v[190:191], v[190:191], v[198:199]
	v_cmp_lt_u32_e32 vcc, 14, v173
	s_and_b64 exec, exec, vcc
	v_lshlrev_b32_e32 v198, 16, v164
	v_and_b32_e32 v199, 0xffff0000, v164
	v_lshlrev_b32_e32 v196, 16, v165
	v_and_b32_e32 v197, 0xffff0000, v165
	v_lshlrev_b32_e32 v194, 16, v166
	v_and_b32_e32 v195, 0xffff0000, v166
	v_lshlrev_b32_e32 v192, 16, v167
	v_and_b32_e32 v193, 0xffff0000, v167
	v_pk_add_f32 v[184:185], v[184:185], v[192:193]
	v_pk_add_f32 v[186:187], v[186:187], v[194:195]
	v_pk_add_f32 v[188:189], v[188:189], v[196:197]
	v_pk_add_f32 v[190:191], v[190:191], v[198:199]
	v_cmp_lt_u32_e32 vcc, 15, v173
	s_and_b64 exec, exec, vcc
	v_lshlrev_b32_e32 v198, 16, v168
	v_and_b32_e32 v199, 0xffff0000, v168
	v_lshlrev_b32_e32 v196, 16, v169
	v_and_b32_e32 v197, 0xffff0000, v169
	v_lshlrev_b32_e32 v194, 16, v170
	v_and_b32_e32 v195, 0xffff0000, v170
	v_lshlrev_b32_e32 v192, 16, v171
	v_and_b32_e32 v193, 0xffff0000, v171
	v_pk_add_f32 v[184:185], v[184:185], v[192:193]
	v_pk_add_f32 v[186:187], v[186:187], v[194:195]
	v_pk_add_f32 v[188:189], v[188:189], v[196:197]
	v_pk_add_f32 v[190:191], v[190:191], v[198:199]
	s_mov_b64 exec, s[26:27]
	v_pk_fma_f32 v[184:185], v[184:185], v[174:175], v[176:177] op_sel_hi:[1,0,1] neg_lo:[0,0,1] neg_hi:[0,0,1]
	v_pk_fma_f32 v[186:187], v[186:187], v[174:175], v[178:179] op_sel_hi:[1,0,1] neg_lo:[0,0,1] neg_hi:[0,0,1]
	v_pk_fma_f32 v[188:189], v[188:189], v[174:175], v[180:181] op_sel_hi:[1,0,1] neg_lo:[0,0,1] neg_hi:[0,0,1]
	v_pk_fma_f32 v[190:191], v[190:191], v[174:175], v[182:183] op_sel_hi:[1,0,1] neg_lo:[0,0,1] neg_hi:[0,0,1]
	v_cvt_pk_bf16_f32 v200, v190, v191
	v_cvt_pk_bf16_f32 v201, v188, v189
	v_cvt_pk_bf16_f32 v202, v186, v187
	v_cvt_pk_bf16_f32 v203, v184, v185
	s_lshl_b32 s21, s22, 10
	s_add_u32 s24, s88, s21
	s_addc_u32 s25, s89, 0
	global_store_dwordx4 v175, v[200:203], s[24:25]
	s_add_i32 s22, s22, 0x800
	s_add_i32 s20, s20, 0x800
	s_mov_b32 s21, s20
	s_max_i32 s21, s21, 0
	s_mul_i32 s21, s21, 0x1200
	s_add_u32 s24, s90, s21
	s_addc_u32 s25, s91, 0
	global_load_dwordx4 v[108:111], v172, s[24:25]
	s_sub_i32 s21, s20, 1
	s_max_i32 s21, s21, 0
	s_mul_i32 s21, s21, 0x1200
	s_add_u32 s24, s90, s21
	s_addc_u32 s25, s91, 0
	global_load_dwordx4 v[112:115], v172, s[24:25]
	s_sub_i32 s21, s20, 2
	s_max_i32 s21, s21, 0
	s_mul_i32 s21, s21, 0x1200
	s_add_u32 s24, s90, s21
	s_addc_u32 s25, s91, 0
	global_load_dwordx4 v[116:119], v172, s[24:25]
	s_sub_i32 s21, s20, 3
	s_max_i32 s21, s21, 0
	s_mul_i32 s21, s21, 0x1200
	s_add_u32 s24, s90, s21
	s_addc_u32 s25, s91, 0
	global_load_dwordx4 v[120:123], v172, s[24:25]
	s_sub_i32 s21, s20, 4
	s_max_i32 s21, s21, 0
	s_mul_i32 s21, s21, 0x1200
	s_add_u32 s24, s90, s21
	s_addc_u32 s25, s91, 0
	global_load_dwordx4 v[124:127], v172, s[24:25]
	s_sub_i32 s21, s20, 5
	s_max_i32 s21, s21, 0
	s_mul_i32 s21, s21, 0x1200
	s_add_u32 s24, s90, s21
	s_addc_u32 s25, s91, 0
	global_load_dwordx4 v[128:131], v172, s[24:25]
	s_sub_i32 s21, s20, 6
	s_max_i32 s21, s21, 0
	s_mul_i32 s21, s21, 0x1200
	s_add_u32 s24, s90, s21
	s_addc_u32 s25, s91, 0
	global_load_dwordx4 v[132:135], v172, s[24:25]
	s_sub_i32 s21, s20, 7
	s_max_i32 s21, s21, 0
	s_mul_i32 s21, s21, 0x1200
	s_add_u32 s24, s90, s21
	s_addc_u32 s25, s91, 0
	global_load_dwordx4 v[136:139], v172, s[24:25]
	s_sub_i32 s21, s20, 8
	s_max_i32 s21, s21, 0
	s_mul_i32 s21, s21, 0x1200
	s_add_u32 s24, s90, s21
	s_addc_u32 s25, s91, 0
	global_load_dwordx4 v[140:143], v172, s[24:25]
	s_sub_i32 s21, s20, 9
	s_max_i32 s21, s21, 0
	s_mul_i32 s21, s21, 0x1200
	s_add_u32 s24, s90, s21
	s_addc_u32 s25, s91, 0
	global_load_dwordx4 v[144:147], v172, s[24:25]
	s_sub_i32 s21, s20, 10
	s_max_i32 s21, s21, 0
	s_mul_i32 s21, s21, 0x1200
	s_add_u32 s24, s90, s21
	s_addc_u32 s25, s91, 0
	global_load_dwordx4 v[148:151], v172, s[24:25]
	s_sub_i32 s21, s20, 11
	s_max_i32 s21, s21, 0
	s_mul_i32 s21, s21, 0x1200
	s_add_u32 s24, s90, s21
	s_addc_u32 s25, s91, 0
	global_load_dwordx4 v[152:155], v172, s[24:25]
	s_sub_i32 s21, s20, 12
	s_max_i32 s21, s21, 0
	s_mul_i32 s21, s21, 0x1200
	s_add_u32 s24, s90, s21
	s_addc_u32 s25, s91, 0
	global_load_dwordx4 v[156:159], v172, s[24:25]
	s_sub_i32 s21, s20, 13
	s_max_i32 s21, s21, 0
	s_mul_i32 s21, s21, 0x1200
	s_add_u32 s24, s90, s21
	s_addc_u32 s25, s91, 0
	global_load_dwordx4 v[160:163], v172, s[24:25]
	s_sub_i32 s21, s20, 14
	s_max_i32 s21, s21, 0
	s_mul_i32 s21, s21, 0x1200
	s_add_u32 s24, s90, s21
	s_addc_u32 s25, s91, 0
	global_load_dwordx4 v[164:167], v172, s[24:25]
	s_sub_i32 s21, s20, 15
	s_max_i32 s21, s21, 0
	s_mul_i32 s21, s21, 0x1200
	s_add_u32 s24, s90, s21
	s_addc_u32 s25, s91, 0
	global_load_dwordx4 v[168:171], v172, s[24:25]
	s_waitcnt vmcnt(17)
	v_lshlrev_b32_e32 v182, 16, v44
	v_and_b32_e32 v183, 0xffff0000, v44
	v_lshlrev_b32_e32 v180, 16, v45
	v_and_b32_e32 v181, 0xffff0000, v45
	v_lshlrev_b32_e32 v178, 16, v46
	v_and_b32_e32 v179, 0xffff0000, v46
	v_lshlrev_b32_e32 v176, 16, v47
	v_and_b32_e32 v177, 0xffff0000, v47
	v_mov_b32_e32 v184, v176
	v_mov_b32_e32 v185, v177
	v_mov_b32_e32 v186, v178
	v_mov_b32_e32 v187, v179
	v_mov_b32_e32 v188, v180
	v_mov_b32_e32 v189, v181
	v_mov_b32_e32 v190, v182
	v_mov_b32_e32 v191, v183
	s_mov_b64 s[26:27], exec
	v_cmp_lt_u32_e32 vcc, 1, v173
	s_and_b64 exec, exec, vcc
	v_lshlrev_b32_e32 v198, 16, v48
	v_and_b32_e32 v199, 0xffff0000, v48
	v_lshlrev_b32_e32 v196, 16, v49
	v_and_b32_e32 v197, 0xffff0000, v49
	v_lshlrev_b32_e32 v194, 16, v50
	v_and_b32_e32 v195, 0xffff0000, v50
	v_lshlrev_b32_e32 v192, 16, v51
	v_and_b32_e32 v193, 0xffff0000, v51
	v_pk_add_f32 v[184:185], v[184:185], v[192:193]
	v_pk_add_f32 v[186:187], v[186:187], v[194:195]
	v_pk_add_f32 v[188:189], v[188:189], v[196:197]
	v_pk_add_f32 v[190:191], v[190:191], v[198:199]
	v_cmp_lt_u32_e32 vcc, 2, v173
	s_and_b64 exec, exec, vcc
	v_lshlrev_b32_e32 v198, 16, v52
	v_and_b32_e32 v199, 0xffff0000, v52
	v_lshlrev_b32_e32 v196, 16, v53
	v_and_b32_e32 v197, 0xffff0000, v53
	v_lshlrev_b32_e32 v194, 16, v54
	v_and_b32_e32 v195, 0xffff0000, v54
	v_lshlrev_b32_e32 v192, 16, v55
	v_and_b32_e32 v193, 0xffff0000, v55
	v_pk_add_f32 v[184:185], v[184:185], v[192:193]
	v_pk_add_f32 v[186:187], v[186:187], v[194:195]
	v_pk_add_f32 v[188:189], v[188:189], v[196:197]
	v_pk_add_f32 v[190:191], v[190:191], v[198:199]
	v_cmp_lt_u32_e32 vcc, 3, v173
	s_and_b64 exec, exec, vcc
	v_lshlrev_b32_e32 v198, 16, v56
	v_and_b32_e32 v199, 0xffff0000, v56
	v_lshlrev_b32_e32 v196, 16, v57
	v_and_b32_e32 v197, 0xffff0000, v57
	v_lshlrev_b32_e32 v194, 16, v58
	v_and_b32_e32 v195, 0xffff0000, v58
	v_lshlrev_b32_e32 v192, 16, v59
	v_and_b32_e32 v193, 0xffff0000, v59
	v_pk_add_f32 v[184:185], v[184:185], v[192:193]
	v_pk_add_f32 v[186:187], v[186:187], v[194:195]
	v_pk_add_f32 v[188:189], v[188:189], v[196:197]
	v_pk_add_f32 v[190:191], v[190:191], v[198:199]
	v_cmp_lt_u32_e32 vcc, 4, v173
	s_and_b64 exec, exec, vcc
	v_lshlrev_b32_e32 v198, 16, v60
	v_and_b32_e32 v199, 0xffff0000, v60
	v_lshlrev_b32_e32 v196, 16, v61
	v_and_b32_e32 v197, 0xffff0000, v61
	v_lshlrev_b32_e32 v194, 16, v62
	v_and_b32_e32 v195, 0xffff0000, v62
	v_lshlrev_b32_e32 v192, 16, v63
	v_and_b32_e32 v193, 0xffff0000, v63
	v_pk_add_f32 v[184:185], v[184:185], v[192:193]
	v_pk_add_f32 v[186:187], v[186:187], v[194:195]
	v_pk_add_f32 v[188:189], v[188:189], v[196:197]
	v_pk_add_f32 v[190:191], v[190:191], v[198:199]
	v_cmp_lt_u32_e32 vcc, 5, v173
	s_and_b64 exec, exec, vcc
	v_lshlrev_b32_e32 v198, 16, v64
	v_and_b32_e32 v199, 0xffff0000, v64
	v_lshlrev_b32_e32 v196, 16, v65
	v_and_b32_e32 v197, 0xffff0000, v65
	v_lshlrev_b32_e32 v194, 16, v66
	v_and_b32_e32 v195, 0xffff0000, v66
	v_lshlrev_b32_e32 v192, 16, v67
	v_and_b32_e32 v193, 0xffff0000, v67
	v_pk_add_f32 v[184:185], v[184:185], v[192:193]
	v_pk_add_f32 v[186:187], v[186:187], v[194:195]
	v_pk_add_f32 v[188:189], v[188:189], v[196:197]
	v_pk_add_f32 v[190:191], v[190:191], v[198:199]
	v_cmp_lt_u32_e32 vcc, 6, v173
	s_and_b64 exec, exec, vcc
	v_lshlrev_b32_e32 v198, 16, v68
	v_and_b32_e32 v199, 0xffff0000, v68
	v_lshlrev_b32_e32 v196, 16, v69
	v_and_b32_e32 v197, 0xffff0000, v69
	v_lshlrev_b32_e32 v194, 16, v70
	v_and_b32_e32 v195, 0xffff0000, v70
	v_lshlrev_b32_e32 v192, 16, v71
	v_and_b32_e32 v193, 0xffff0000, v71
	v_pk_add_f32 v[184:185], v[184:185], v[192:193]
	v_pk_add_f32 v[186:187], v[186:187], v[194:195]
	v_pk_add_f32 v[188:189], v[188:189], v[196:197]
	v_pk_add_f32 v[190:191], v[190:191], v[198:199]
	v_cmp_lt_u32_e32 vcc, 7, v173
	s_and_b64 exec, exec, vcc
	v_lshlrev_b32_e32 v198, 16, v72
	v_and_b32_e32 v199, 0xffff0000, v72
	v_lshlrev_b32_e32 v196, 16, v73
	v_and_b32_e32 v197, 0xffff0000, v73
	v_lshlrev_b32_e32 v194, 16, v74
	v_and_b32_e32 v195, 0xffff0000, v74
	v_lshlrev_b32_e32 v192, 16, v75
	v_and_b32_e32 v193, 0xffff0000, v75
	v_pk_add_f32 v[184:185], v[184:185], v[192:193]
	v_pk_add_f32 v[186:187], v[186:187], v[194:195]
	v_pk_add_f32 v[188:189], v[188:189], v[196:197]
	v_pk_add_f32 v[190:191], v[190:191], v[198:199]
	v_cmp_lt_u32_e32 vcc, 8, v173
	s_and_b64 exec, exec, vcc
	v_lshlrev_b32_e32 v198, 16, v76
	v_and_b32_e32 v199, 0xffff0000, v76
	v_lshlrev_b32_e32 v196, 16, v77
	v_and_b32_e32 v197, 0xffff0000, v77
	v_lshlrev_b32_e32 v194, 16, v78
	v_and_b32_e32 v195, 0xffff0000, v78
	v_lshlrev_b32_e32 v192, 16, v79
	v_and_b32_e32 v193, 0xffff0000, v79
	v_pk_add_f32 v[184:185], v[184:185], v[192:193]
	v_pk_add_f32 v[186:187], v[186:187], v[194:195]
	v_pk_add_f32 v[188:189], v[188:189], v[196:197]
	v_pk_add_f32 v[190:191], v[190:191], v[198:199]
	v_cmp_lt_u32_e32 vcc, 9, v173
	s_and_b64 exec, exec, vcc
	v_lshlrev_b32_e32 v198, 16, v80
	v_and_b32_e32 v199, 0xffff0000, v80
	v_lshlrev_b32_e32 v196, 16, v81
	v_and_b32_e32 v197, 0xffff0000, v81
	v_lshlrev_b32_e32 v194, 16, v82
	v_and_b32_e32 v195, 0xffff0000, v82
	v_lshlrev_b32_e32 v192, 16, v83
	v_and_b32_e32 v193, 0xffff0000, v83
	v_pk_add_f32 v[184:185], v[184:185], v[192:193]
	v_pk_add_f32 v[186:187], v[186:187], v[194:195]
	v_pk_add_f32 v[188:189], v[188:189], v[196:197]
	v_pk_add_f32 v[190:191], v[190:191], v[198:199]
	v_cmp_lt_u32_e32 vcc, 10, v173
	s_and_b64 exec, exec, vcc
	v_lshlrev_b32_e32 v198, 16, v84
	v_and_b32_e32 v199, 0xffff0000, v84
	v_lshlrev_b32_e32 v196, 16, v85
	v_and_b32_e32 v197, 0xffff0000, v85
	v_lshlrev_b32_e32 v194, 16, v86
	v_and_b32_e32 v195, 0xffff0000, v86
	v_lshlrev_b32_e32 v192, 16, v87
	v_and_b32_e32 v193, 0xffff0000, v87
	v_pk_add_f32 v[184:185], v[184:185], v[192:193]
	v_pk_add_f32 v[186:187], v[186:187], v[194:195]
	v_pk_add_f32 v[188:189], v[188:189], v[196:197]
	v_pk_add_f32 v[190:191], v[190:191], v[198:199]
	v_cmp_lt_u32_e32 vcc, 11, v173
	s_and_b64 exec, exec, vcc
	v_lshlrev_b32_e32 v198, 16, v88
	v_and_b32_e32 v199, 0xffff0000, v88
	v_lshlrev_b32_e32 v196, 16, v89
	v_and_b32_e32 v197, 0xffff0000, v89
	v_lshlrev_b32_e32 v194, 16, v90
	v_and_b32_e32 v195, 0xffff0000, v90
	v_lshlrev_b32_e32 v192, 16, v91
	v_and_b32_e32 v193, 0xffff0000, v91
	v_pk_add_f32 v[184:185], v[184:185], v[192:193]
	v_pk_add_f32 v[186:187], v[186:187], v[194:195]
	v_pk_add_f32 v[188:189], v[188:189], v[196:197]
	v_pk_add_f32 v[190:191], v[190:191], v[198:199]
	v_cmp_lt_u32_e32 vcc, 12, v173
	s_and_b64 exec, exec, vcc
	v_lshlrev_b32_e32 v198, 16, v92
	v_and_b32_e32 v199, 0xffff0000, v92
	v_lshlrev_b32_e32 v196, 16, v93
	v_and_b32_e32 v197, 0xffff0000, v93
	v_lshlrev_b32_e32 v194, 16, v94
	v_and_b32_e32 v195, 0xffff0000, v94
	v_lshlrev_b32_e32 v192, 16, v95
	v_and_b32_e32 v193, 0xffff0000, v95
	v_pk_add_f32 v[184:185], v[184:185], v[192:193]
	v_pk_add_f32 v[186:187], v[186:187], v[194:195]
	v_pk_add_f32 v[188:189], v[188:189], v[196:197]
	v_pk_add_f32 v[190:191], v[190:191], v[198:199]
	v_cmp_lt_u32_e32 vcc, 13, v173
	s_and_b64 exec, exec, vcc
	v_lshlrev_b32_e32 v198, 16, v96
	v_and_b32_e32 v199, 0xffff0000, v96
	v_lshlrev_b32_e32 v196, 16, v97
	v_and_b32_e32 v197, 0xffff0000, v97
	v_lshlrev_b32_e32 v194, 16, v98
	v_and_b32_e32 v195, 0xffff0000, v98
	v_lshlrev_b32_e32 v192, 16, v99
	v_and_b32_e32 v193, 0xffff0000, v99
	v_pk_add_f32 v[184:185], v[184:185], v[192:193]
	v_pk_add_f32 v[186:187], v[186:187], v[194:195]
	v_pk_add_f32 v[188:189], v[188:189], v[196:197]
	v_pk_add_f32 v[190:191], v[190:191], v[198:199]
	v_cmp_lt_u32_e32 vcc, 14, v173
	s_and_b64 exec, exec, vcc
	v_lshlrev_b32_e32 v198, 16, v100
	v_and_b32_e32 v199, 0xffff0000, v100
	v_lshlrev_b32_e32 v196, 16, v101
	v_and_b32_e32 v197, 0xffff0000, v101
	v_lshlrev_b32_e32 v194, 16, v102
	v_and_b32_e32 v195, 0xffff0000, v102
	v_lshlrev_b32_e32 v192, 16, v103
	v_and_b32_e32 v193, 0xffff0000, v103
	v_pk_add_f32 v[184:185], v[184:185], v[192:193]
	v_pk_add_f32 v[186:187], v[186:187], v[194:195]
	v_pk_add_f32 v[188:189], v[188:189], v[196:197]
	v_pk_add_f32 v[190:191], v[190:191], v[198:199]
	v_cmp_lt_u32_e32 vcc, 15, v173
	s_and_b64 exec, exec, vcc
	v_lshlrev_b32_e32 v198, 16, v104
	v_and_b32_e32 v199, 0xffff0000, v104
	v_lshlrev_b32_e32 v196, 16, v105
	v_and_b32_e32 v197, 0xffff0000, v105
	v_lshlrev_b32_e32 v194, 16, v106
	v_and_b32_e32 v195, 0xffff0000, v106
	v_lshlrev_b32_e32 v192, 16, v107
	v_and_b32_e32 v193, 0xffff0000, v107
	v_pk_add_f32 v[184:185], v[184:185], v[192:193]
	v_pk_add_f32 v[186:187], v[186:187], v[194:195]
	v_pk_add_f32 v[188:189], v[188:189], v[196:197]
	v_pk_add_f32 v[190:191], v[190:191], v[198:199]
	s_mov_b64 exec, s[26:27]
	v_pk_fma_f32 v[184:185], v[184:185], v[174:175], v[176:177] op_sel_hi:[1,0,1] neg_lo:[0,0,1] neg_hi:[0,0,1]
	v_pk_fma_f32 v[186:187], v[186:187], v[174:175], v[178:179] op_sel_hi:[1,0,1] neg_lo:[0,0,1] neg_hi:[0,0,1]
	v_pk_fma_f32 v[188:189], v[188:189], v[174:175], v[180:181] op_sel_hi:[1,0,1] neg_lo:[0,0,1] neg_hi:[0,0,1]
	v_pk_fma_f32 v[190:191], v[190:191], v[174:175], v[182:183] op_sel_hi:[1,0,1] neg_lo:[0,0,1] neg_hi:[0,0,1]
	v_cvt_pk_bf16_f32 v200, v190, v191
	v_cvt_pk_bf16_f32 v201, v188, v189
	v_cvt_pk_bf16_f32 v202, v186, v187
	v_cvt_pk_bf16_f32 v203, v184, v185
	s_lshl_b32 s21, s22, 10
	s_add_u32 s24, s88, s21
	s_addc_u32 s25, s89, 0
	global_store_dwordx4 v175, v[200:203], s[24:25]
	s_add_i32 s22, s22, 0x800
	s_add_i32 s20, s20, 0x800
	s_mov_b32 s21, s20
	s_max_i32 s21, s21, 0
	s_mul_i32 s21, s21, 0x1200
	s_add_u32 s24, s90, s21
	s_addc_u32 s25, s91, 0
	global_load_dwordx4 v[44:47], v172, s[24:25]
	s_sub_i32 s21, s20, 1
	s_max_i32 s21, s21, 0
	s_mul_i32 s21, s21, 0x1200
	s_add_u32 s24, s90, s21
	s_addc_u32 s25, s91, 0
	global_load_dwordx4 v[48:51], v172, s[24:25]
	s_sub_i32 s21, s20, 2
	s_max_i32 s21, s21, 0
	s_mul_i32 s21, s21, 0x1200
	s_add_u32 s24, s90, s21
	s_addc_u32 s25, s91, 0
	global_load_dwordx4 v[52:55], v172, s[24:25]
	s_sub_i32 s21, s20, 3
	s_max_i32 s21, s21, 0
	s_mul_i32 s21, s21, 0x1200
	s_add_u32 s24, s90, s21
	s_addc_u32 s25, s91, 0
	global_load_dwordx4 v[56:59], v172, s[24:25]
	s_sub_i32 s21, s20, 4
	s_max_i32 s21, s21, 0
	s_mul_i32 s21, s21, 0x1200
	s_add_u32 s24, s90, s21
	s_addc_u32 s25, s91, 0
	global_load_dwordx4 v[60:63], v172, s[24:25]
	s_sub_i32 s21, s20, 5
	s_max_i32 s21, s21, 0
	s_mul_i32 s21, s21, 0x1200
	s_add_u32 s24, s90, s21
	s_addc_u32 s25, s91, 0
	global_load_dwordx4 v[64:67], v172, s[24:25]
	s_sub_i32 s21, s20, 6
	s_max_i32 s21, s21, 0
	s_mul_i32 s21, s21, 0x1200
	s_add_u32 s24, s90, s21
	s_addc_u32 s25, s91, 0
	global_load_dwordx4 v[68:71], v172, s[24:25]
	s_sub_i32 s21, s20, 7
	s_max_i32 s21, s21, 0
	s_mul_i32 s21, s21, 0x1200
	s_add_u32 s24, s90, s21
	s_addc_u32 s25, s91, 0
	global_load_dwordx4 v[72:75], v172, s[24:25]
	s_sub_i32 s21, s20, 8
	s_max_i32 s21, s21, 0
	s_mul_i32 s21, s21, 0x1200
	s_add_u32 s24, s90, s21
	s_addc_u32 s25, s91, 0
	global_load_dwordx4 v[76:79], v172, s[24:25]
	s_sub_i32 s21, s20, 9
	s_max_i32 s21, s21, 0
	s_mul_i32 s21, s21, 0x1200
	s_add_u32 s24, s90, s21
	s_addc_u32 s25, s91, 0
	global_load_dwordx4 v[80:83], v172, s[24:25]
	s_sub_i32 s21, s20, 10
	s_max_i32 s21, s21, 0
	s_mul_i32 s21, s21, 0x1200
	s_add_u32 s24, s90, s21
	s_addc_u32 s25, s91, 0
	global_load_dwordx4 v[84:87], v172, s[24:25]
	s_sub_i32 s21, s20, 11
	s_max_i32 s21, s21, 0
	s_mul_i32 s21, s21, 0x1200
	s_add_u32 s24, s90, s21
	s_addc_u32 s25, s91, 0
	global_load_dwordx4 v[88:91], v172, s[24:25]
	s_sub_i32 s21, s20, 12
	s_max_i32 s21, s21, 0
	s_mul_i32 s21, s21, 0x1200
	s_add_u32 s24, s90, s21
	s_addc_u32 s25, s91, 0
	global_load_dwordx4 v[92:95], v172, s[24:25]
	s_sub_i32 s21, s20, 13
	s_max_i32 s21, s21, 0
	s_mul_i32 s21, s21, 0x1200
	s_add_u32 s24, s90, s21
	s_addc_u32 s25, s91, 0
	global_load_dwordx4 v[96:99], v172, s[24:25]
	s_sub_i32 s21, s20, 14
	s_max_i32 s21, s21, 0
	s_mul_i32 s21, s21, 0x1200
	s_add_u32 s24, s90, s21
	s_addc_u32 s25, s91, 0
	global_load_dwordx4 v[100:103], v172, s[24:25]
	s_sub_i32 s21, s20, 15
	s_max_i32 s21, s21, 0
	s_mul_i32 s21, s21, 0x1200
	s_add_u32 s24, s90, s21
	s_addc_u32 s25, s91, 0
	global_load_dwordx4 v[104:107], v172, s[24:25]
	s_waitcnt vmcnt(17)
	v_lshlrev_b32_e32 v182, 16, v108
	v_and_b32_e32 v183, 0xffff0000, v108
	v_lshlrev_b32_e32 v180, 16, v109
	v_and_b32_e32 v181, 0xffff0000, v109
	v_lshlrev_b32_e32 v178, 16, v110
	v_and_b32_e32 v179, 0xffff0000, v110
	v_lshlrev_b32_e32 v176, 16, v111
	v_and_b32_e32 v177, 0xffff0000, v111
	v_mov_b32_e32 v184, v176
	v_mov_b32_e32 v185, v177
	v_mov_b32_e32 v186, v178
	v_mov_b32_e32 v187, v179
	v_mov_b32_e32 v188, v180
	v_mov_b32_e32 v189, v181
	v_mov_b32_e32 v190, v182
	v_mov_b32_e32 v191, v183
	s_mov_b64 s[26:27], exec
	v_cmp_lt_u32_e32 vcc, 1, v173
	s_and_b64 exec, exec, vcc
	v_lshlrev_b32_e32 v198, 16, v112
	v_and_b32_e32 v199, 0xffff0000, v112
	v_lshlrev_b32_e32 v196, 16, v113
	v_and_b32_e32 v197, 0xffff0000, v113
	v_lshlrev_b32_e32 v194, 16, v114
	v_and_b32_e32 v195, 0xffff0000, v114
	v_lshlrev_b32_e32 v192, 16, v115
	v_and_b32_e32 v193, 0xffff0000, v115
	v_pk_add_f32 v[184:185], v[184:185], v[192:193]
	v_pk_add_f32 v[186:187], v[186:187], v[194:195]
	v_pk_add_f32 v[188:189], v[188:189], v[196:197]
	v_pk_add_f32 v[190:191], v[190:191], v[198:199]
	v_cmp_lt_u32_e32 vcc, 2, v173
	s_and_b64 exec, exec, vcc
	v_lshlrev_b32_e32 v198, 16, v116
	v_and_b32_e32 v199, 0xffff0000, v116
	v_lshlrev_b32_e32 v196, 16, v117
	v_and_b32_e32 v197, 0xffff0000, v117
	v_lshlrev_b32_e32 v194, 16, v118
	v_and_b32_e32 v195, 0xffff0000, v118
	v_lshlrev_b32_e32 v192, 16, v119
	v_and_b32_e32 v193, 0xffff0000, v119
	v_pk_add_f32 v[184:185], v[184:185], v[192:193]
	v_pk_add_f32 v[186:187], v[186:187], v[194:195]
	v_pk_add_f32 v[188:189], v[188:189], v[196:197]
	v_pk_add_f32 v[190:191], v[190:191], v[198:199]
	v_cmp_lt_u32_e32 vcc, 3, v173
	s_and_b64 exec, exec, vcc
	v_lshlrev_b32_e32 v198, 16, v120
	v_and_b32_e32 v199, 0xffff0000, v120
	v_lshlrev_b32_e32 v196, 16, v121
	v_and_b32_e32 v197, 0xffff0000, v121
	v_lshlrev_b32_e32 v194, 16, v122
	v_and_b32_e32 v195, 0xffff0000, v122
	v_lshlrev_b32_e32 v192, 16, v123
	v_and_b32_e32 v193, 0xffff0000, v123
	v_pk_add_f32 v[184:185], v[184:185], v[192:193]
	v_pk_add_f32 v[186:187], v[186:187], v[194:195]
	v_pk_add_f32 v[188:189], v[188:189], v[196:197]
	v_pk_add_f32 v[190:191], v[190:191], v[198:199]
	v_cmp_lt_u32_e32 vcc, 4, v173
	s_and_b64 exec, exec, vcc
	v_lshlrev_b32_e32 v198, 16, v124
	v_and_b32_e32 v199, 0xffff0000, v124
	v_lshlrev_b32_e32 v196, 16, v125
	v_and_b32_e32 v197, 0xffff0000, v125
	v_lshlrev_b32_e32 v194, 16, v126
	v_and_b32_e32 v195, 0xffff0000, v126
	v_lshlrev_b32_e32 v192, 16, v127
	v_and_b32_e32 v193, 0xffff0000, v127
	v_pk_add_f32 v[184:185], v[184:185], v[192:193]
	v_pk_add_f32 v[186:187], v[186:187], v[194:195]
	v_pk_add_f32 v[188:189], v[188:189], v[196:197]
	v_pk_add_f32 v[190:191], v[190:191], v[198:199]
	v_cmp_lt_u32_e32 vcc, 5, v173
	s_and_b64 exec, exec, vcc
	v_lshlrev_b32_e32 v198, 16, v128
	v_and_b32_e32 v199, 0xffff0000, v128
	v_lshlrev_b32_e32 v196, 16, v129
	v_and_b32_e32 v197, 0xffff0000, v129
	v_lshlrev_b32_e32 v194, 16, v130
	v_and_b32_e32 v195, 0xffff0000, v130
	v_lshlrev_b32_e32 v192, 16, v131
	v_and_b32_e32 v193, 0xffff0000, v131
	v_pk_add_f32 v[184:185], v[184:185], v[192:193]
	v_pk_add_f32 v[186:187], v[186:187], v[194:195]
	v_pk_add_f32 v[188:189], v[188:189], v[196:197]
	v_pk_add_f32 v[190:191], v[190:191], v[198:199]
	v_cmp_lt_u32_e32 vcc, 6, v173
	s_and_b64 exec, exec, vcc
	v_lshlrev_b32_e32 v198, 16, v132
	v_and_b32_e32 v199, 0xffff0000, v132
	v_lshlrev_b32_e32 v196, 16, v133
	v_and_b32_e32 v197, 0xffff0000, v133
	v_lshlrev_b32_e32 v194, 16, v134
	v_and_b32_e32 v195, 0xffff0000, v134
	v_lshlrev_b32_e32 v192, 16, v135
	v_and_b32_e32 v193, 0xffff0000, v135
	v_pk_add_f32 v[184:185], v[184:185], v[192:193]
	v_pk_add_f32 v[186:187], v[186:187], v[194:195]
	v_pk_add_f32 v[188:189], v[188:189], v[196:197]
	v_pk_add_f32 v[190:191], v[190:191], v[198:199]
	v_cmp_lt_u32_e32 vcc, 7, v173
	s_and_b64 exec, exec, vcc
	v_lshlrev_b32_e32 v198, 16, v136
	v_and_b32_e32 v199, 0xffff0000, v136
	v_lshlrev_b32_e32 v196, 16, v137
	v_and_b32_e32 v197, 0xffff0000, v137
	v_lshlrev_b32_e32 v194, 16, v138
	v_and_b32_e32 v195, 0xffff0000, v138
	v_lshlrev_b32_e32 v192, 16, v139
	v_and_b32_e32 v193, 0xffff0000, v139
	v_pk_add_f32 v[184:185], v[184:185], v[192:193]
	v_pk_add_f32 v[186:187], v[186:187], v[194:195]
	v_pk_add_f32 v[188:189], v[188:189], v[196:197]
	v_pk_add_f32 v[190:191], v[190:191], v[198:199]
	v_cmp_lt_u32_e32 vcc, 8, v173
	s_and_b64 exec, exec, vcc
	v_lshlrev_b32_e32 v198, 16, v140
	v_and_b32_e32 v199, 0xffff0000, v140
	v_lshlrev_b32_e32 v196, 16, v141
	v_and_b32_e32 v197, 0xffff0000, v141
	v_lshlrev_b32_e32 v194, 16, v142
	v_and_b32_e32 v195, 0xffff0000, v142
	v_lshlrev_b32_e32 v192, 16, v143
	v_and_b32_e32 v193, 0xffff0000, v143
	v_pk_add_f32 v[184:185], v[184:185], v[192:193]
	v_pk_add_f32 v[186:187], v[186:187], v[194:195]
	v_pk_add_f32 v[188:189], v[188:189], v[196:197]
	v_pk_add_f32 v[190:191], v[190:191], v[198:199]
	v_cmp_lt_u32_e32 vcc, 9, v173
	s_and_b64 exec, exec, vcc
	v_lshlrev_b32_e32 v198, 16, v144
	v_and_b32_e32 v199, 0xffff0000, v144
	v_lshlrev_b32_e32 v196, 16, v145
	v_and_b32_e32 v197, 0xffff0000, v145
	v_lshlrev_b32_e32 v194, 16, v146
	v_and_b32_e32 v195, 0xffff0000, v146
	v_lshlrev_b32_e32 v192, 16, v147
	v_and_b32_e32 v193, 0xffff0000, v147
	v_pk_add_f32 v[184:185], v[184:185], v[192:193]
	v_pk_add_f32 v[186:187], v[186:187], v[194:195]
	v_pk_add_f32 v[188:189], v[188:189], v[196:197]
	v_pk_add_f32 v[190:191], v[190:191], v[198:199]
	v_cmp_lt_u32_e32 vcc, 10, v173
	s_and_b64 exec, exec, vcc
	v_lshlrev_b32_e32 v198, 16, v148
	v_and_b32_e32 v199, 0xffff0000, v148
	v_lshlrev_b32_e32 v196, 16, v149
	v_and_b32_e32 v197, 0xffff0000, v149
	v_lshlrev_b32_e32 v194, 16, v150
	v_and_b32_e32 v195, 0xffff0000, v150
	v_lshlrev_b32_e32 v192, 16, v151
	v_and_b32_e32 v193, 0xffff0000, v151
	v_pk_add_f32 v[184:185], v[184:185], v[192:193]
	v_pk_add_f32 v[186:187], v[186:187], v[194:195]
	v_pk_add_f32 v[188:189], v[188:189], v[196:197]
	v_pk_add_f32 v[190:191], v[190:191], v[198:199]
	v_cmp_lt_u32_e32 vcc, 11, v173
	s_and_b64 exec, exec, vcc
	v_lshlrev_b32_e32 v198, 16, v152
	v_and_b32_e32 v199, 0xffff0000, v152
	v_lshlrev_b32_e32 v196, 16, v153
	v_and_b32_e32 v197, 0xffff0000, v153
	v_lshlrev_b32_e32 v194, 16, v154
	v_and_b32_e32 v195, 0xffff0000, v154
	v_lshlrev_b32_e32 v192, 16, v155
	v_and_b32_e32 v193, 0xffff0000, v155
	v_pk_add_f32 v[184:185], v[184:185], v[192:193]
	v_pk_add_f32 v[186:187], v[186:187], v[194:195]
	v_pk_add_f32 v[188:189], v[188:189], v[196:197]
	v_pk_add_f32 v[190:191], v[190:191], v[198:199]
	v_cmp_lt_u32_e32 vcc, 12, v173
	s_and_b64 exec, exec, vcc
	v_lshlrev_b32_e32 v198, 16, v156
	v_and_b32_e32 v199, 0xffff0000, v156
	v_lshlrev_b32_e32 v196, 16, v157
	v_and_b32_e32 v197, 0xffff0000, v157
	v_lshlrev_b32_e32 v194, 16, v158
	v_and_b32_e32 v195, 0xffff0000, v158
	v_lshlrev_b32_e32 v192, 16, v159
	v_and_b32_e32 v193, 0xffff0000, v159
	v_pk_add_f32 v[184:185], v[184:185], v[192:193]
	v_pk_add_f32 v[186:187], v[186:187], v[194:195]
	v_pk_add_f32 v[188:189], v[188:189], v[196:197]
	v_pk_add_f32 v[190:191], v[190:191], v[198:199]
	v_cmp_lt_u32_e32 vcc, 13, v173
	s_and_b64 exec, exec, vcc
	v_lshlrev_b32_e32 v198, 16, v160
	v_and_b32_e32 v199, 0xffff0000, v160
	v_lshlrev_b32_e32 v196, 16, v161
	v_and_b32_e32 v197, 0xffff0000, v161
	v_lshlrev_b32_e32 v194, 16, v162
	v_and_b32_e32 v195, 0xffff0000, v162
	v_lshlrev_b32_e32 v192, 16, v163
	v_and_b32_e32 v193, 0xffff0000, v163
	v_pk_add_f32 v[184:185], v[184:185], v[192:193]
	v_pk_add_f32 v[186:187], v[186:187], v[194:195]
	v_pk_add_f32 v[188:189], v[188:189], v[196:197]
	v_pk_add_f32 v[190:191], v[190:191], v[198:199]
	v_cmp_lt_u32_e32 vcc, 14, v173
	s_and_b64 exec, exec, vcc
	v_lshlrev_b32_e32 v198, 16, v164
	v_and_b32_e32 v199, 0xffff0000, v164
	v_lshlrev_b32_e32 v196, 16, v165
	v_and_b32_e32 v197, 0xffff0000, v165
	v_lshlrev_b32_e32 v194, 16, v166
	v_and_b32_e32 v195, 0xffff0000, v166
	v_lshlrev_b32_e32 v192, 16, v167
	v_and_b32_e32 v193, 0xffff0000, v167
	v_pk_add_f32 v[184:185], v[184:185], v[192:193]
	v_pk_add_f32 v[186:187], v[186:187], v[194:195]
	v_pk_add_f32 v[188:189], v[188:189], v[196:197]
	v_pk_add_f32 v[190:191], v[190:191], v[198:199]
	v_cmp_lt_u32_e32 vcc, 15, v173
	s_and_b64 exec, exec, vcc
	v_lshlrev_b32_e32 v198, 16, v168
	v_and_b32_e32 v199, 0xffff0000, v168
	v_lshlrev_b32_e32 v196, 16, v169
	v_and_b32_e32 v197, 0xffff0000, v169
	v_lshlrev_b32_e32 v194, 16, v170
	v_and_b32_e32 v195, 0xffff0000, v170
	v_lshlrev_b32_e32 v192, 16, v171
	v_and_b32_e32 v193, 0xffff0000, v171
	v_pk_add_f32 v[184:185], v[184:185], v[192:193]
	v_pk_add_f32 v[186:187], v[186:187], v[194:195]
	v_pk_add_f32 v[188:189], v[188:189], v[196:197]
	v_pk_add_f32 v[190:191], v[190:191], v[198:199]
	s_mov_b64 exec, s[26:27]
	v_pk_fma_f32 v[184:185], v[184:185], v[174:175], v[176:177] op_sel_hi:[1,0,1] neg_lo:[0,0,1] neg_hi:[0,0,1]
	v_pk_fma_f32 v[186:187], v[186:187], v[174:175], v[178:179] op_sel_hi:[1,0,1] neg_lo:[0,0,1] neg_hi:[0,0,1]
	v_pk_fma_f32 v[188:189], v[188:189], v[174:175], v[180:181] op_sel_hi:[1,0,1] neg_lo:[0,0,1] neg_hi:[0,0,1]
	v_pk_fma_f32 v[190:191], v[190:191], v[174:175], v[182:183] op_sel_hi:[1,0,1] neg_lo:[0,0,1] neg_hi:[0,0,1]
	v_cvt_pk_bf16_f32 v200, v190, v191
	v_cvt_pk_bf16_f32 v201, v188, v189
	v_cvt_pk_bf16_f32 v202, v186, v187
	v_cvt_pk_bf16_f32 v203, v184, v185
	s_lshl_b32 s21, s22, 10
	s_add_u32 s24, s88, s21
	s_addc_u32 s25, s89, 0
	global_store_dwordx4 v175, v[200:203], s[24:25]
	s_add_i32 s22, s22, 0x800
	s_add_i32 s20, s20, 0x800
	s_mov_b32 s21, s20
	s_max_i32 s21, s21, 0
	s_mul_i32 s21, s21, 0x1200
	s_add_u32 s24, s90, s21
	s_addc_u32 s25, s91, 0
	global_load_dwordx4 v[108:111], v172, s[24:25]
	s_sub_i32 s21, s20, 1
	s_max_i32 s21, s21, 0
	s_mul_i32 s21, s21, 0x1200
	s_add_u32 s24, s90, s21
	s_addc_u32 s25, s91, 0
	global_load_dwordx4 v[112:115], v172, s[24:25]
	s_sub_i32 s21, s20, 2
	s_max_i32 s21, s21, 0
	s_mul_i32 s21, s21, 0x1200
	s_add_u32 s24, s90, s21
	s_addc_u32 s25, s91, 0
	global_load_dwordx4 v[116:119], v172, s[24:25]
	s_sub_i32 s21, s20, 3
	s_max_i32 s21, s21, 0
	s_mul_i32 s21, s21, 0x1200
	s_add_u32 s24, s90, s21
	s_addc_u32 s25, s91, 0
	global_load_dwordx4 v[120:123], v172, s[24:25]
	s_sub_i32 s21, s20, 4
	s_max_i32 s21, s21, 0
	s_mul_i32 s21, s21, 0x1200
	s_add_u32 s24, s90, s21
	s_addc_u32 s25, s91, 0
	global_load_dwordx4 v[124:127], v172, s[24:25]
	s_sub_i32 s21, s20, 5
	s_max_i32 s21, s21, 0
	s_mul_i32 s21, s21, 0x1200
	s_add_u32 s24, s90, s21
	s_addc_u32 s25, s91, 0
	global_load_dwordx4 v[128:131], v172, s[24:25]
	s_sub_i32 s21, s20, 6
	s_max_i32 s21, s21, 0
	s_mul_i32 s21, s21, 0x1200
	s_add_u32 s24, s90, s21
	s_addc_u32 s25, s91, 0
	global_load_dwordx4 v[132:135], v172, s[24:25]
	s_sub_i32 s21, s20, 7
	s_max_i32 s21, s21, 0
	s_mul_i32 s21, s21, 0x1200
	s_add_u32 s24, s90, s21
	s_addc_u32 s25, s91, 0
	global_load_dwordx4 v[136:139], v172, s[24:25]
	s_sub_i32 s21, s20, 8
	s_max_i32 s21, s21, 0
	s_mul_i32 s21, s21, 0x1200
	s_add_u32 s24, s90, s21
	s_addc_u32 s25, s91, 0
	global_load_dwordx4 v[140:143], v172, s[24:25]
	s_sub_i32 s21, s20, 9
	s_max_i32 s21, s21, 0
	s_mul_i32 s21, s21, 0x1200
	s_add_u32 s24, s90, s21
	s_addc_u32 s25, s91, 0
	global_load_dwordx4 v[144:147], v172, s[24:25]
	s_sub_i32 s21, s20, 10
	s_max_i32 s21, s21, 0
	s_mul_i32 s21, s21, 0x1200
	s_add_u32 s24, s90, s21
	s_addc_u32 s25, s91, 0
	global_load_dwordx4 v[148:151], v172, s[24:25]
	s_sub_i32 s21, s20, 11
	s_max_i32 s21, s21, 0
	s_mul_i32 s21, s21, 0x1200
	s_add_u32 s24, s90, s21
	s_addc_u32 s25, s91, 0
	global_load_dwordx4 v[152:155], v172, s[24:25]
	s_sub_i32 s21, s20, 12
	s_max_i32 s21, s21, 0
	s_mul_i32 s21, s21, 0x1200
	s_add_u32 s24, s90, s21
	s_addc_u32 s25, s91, 0
	global_load_dwordx4 v[156:159], v172, s[24:25]
	s_sub_i32 s21, s20, 13
	s_max_i32 s21, s21, 0
	s_mul_i32 s21, s21, 0x1200
	s_add_u32 s24, s90, s21
	s_addc_u32 s25, s91, 0
	global_load_dwordx4 v[160:163], v172, s[24:25]
	s_sub_i32 s21, s20, 14
	s_max_i32 s21, s21, 0
	s_mul_i32 s21, s21, 0x1200
	s_add_u32 s24, s90, s21
	s_addc_u32 s25, s91, 0
	global_load_dwordx4 v[164:167], v172, s[24:25]
	s_sub_i32 s21, s20, 15
	s_max_i32 s21, s21, 0
	s_mul_i32 s21, s21, 0x1200
	s_add_u32 s24, s90, s21
	s_addc_u32 s25, s91, 0
	global_load_dwordx4 v[168:171], v172, s[24:25]
	s_waitcnt vmcnt(17)
	v_lshlrev_b32_e32 v182, 16, v44
	v_and_b32_e32 v183, 0xffff0000, v44
	v_lshlrev_b32_e32 v180, 16, v45
	v_and_b32_e32 v181, 0xffff0000, v45
	v_lshlrev_b32_e32 v178, 16, v46
	v_and_b32_e32 v179, 0xffff0000, v46
	v_lshlrev_b32_e32 v176, 16, v47
	v_and_b32_e32 v177, 0xffff0000, v47
	v_mov_b32_e32 v184, v176
	v_mov_b32_e32 v185, v177
	v_mov_b32_e32 v186, v178
	v_mov_b32_e32 v187, v179
	v_mov_b32_e32 v188, v180
	v_mov_b32_e32 v189, v181
	v_mov_b32_e32 v190, v182
	v_mov_b32_e32 v191, v183
	s_mov_b64 s[26:27], exec
	v_cmp_lt_u32_e32 vcc, 1, v173
	s_and_b64 exec, exec, vcc
	v_lshlrev_b32_e32 v198, 16, v48
	v_and_b32_e32 v199, 0xffff0000, v48
	v_lshlrev_b32_e32 v196, 16, v49
	v_and_b32_e32 v197, 0xffff0000, v49
	v_lshlrev_b32_e32 v194, 16, v50
	v_and_b32_e32 v195, 0xffff0000, v50
	v_lshlrev_b32_e32 v192, 16, v51
	v_and_b32_e32 v193, 0xffff0000, v51
	v_pk_add_f32 v[184:185], v[184:185], v[192:193]
	v_pk_add_f32 v[186:187], v[186:187], v[194:195]
	v_pk_add_f32 v[188:189], v[188:189], v[196:197]
	v_pk_add_f32 v[190:191], v[190:191], v[198:199]
	v_cmp_lt_u32_e32 vcc, 2, v173
	s_and_b64 exec, exec, vcc
	v_lshlrev_b32_e32 v198, 16, v52
	v_and_b32_e32 v199, 0xffff0000, v52
	v_lshlrev_b32_e32 v196, 16, v53
	v_and_b32_e32 v197, 0xffff0000, v53
	v_lshlrev_b32_e32 v194, 16, v54
	v_and_b32_e32 v195, 0xffff0000, v54
	v_lshlrev_b32_e32 v192, 16, v55
	v_and_b32_e32 v193, 0xffff0000, v55
	v_pk_add_f32 v[184:185], v[184:185], v[192:193]
	v_pk_add_f32 v[186:187], v[186:187], v[194:195]
	v_pk_add_f32 v[188:189], v[188:189], v[196:197]
	v_pk_add_f32 v[190:191], v[190:191], v[198:199]
	v_cmp_lt_u32_e32 vcc, 3, v173
	s_and_b64 exec, exec, vcc
	v_lshlrev_b32_e32 v198, 16, v56
	v_and_b32_e32 v199, 0xffff0000, v56
	v_lshlrev_b32_e32 v196, 16, v57
	v_and_b32_e32 v197, 0xffff0000, v57
	v_lshlrev_b32_e32 v194, 16, v58
	v_and_b32_e32 v195, 0xffff0000, v58
	v_lshlrev_b32_e32 v192, 16, v59
	v_and_b32_e32 v193, 0xffff0000, v59
	v_pk_add_f32 v[184:185], v[184:185], v[192:193]
	v_pk_add_f32 v[186:187], v[186:187], v[194:195]
	v_pk_add_f32 v[188:189], v[188:189], v[196:197]
	v_pk_add_f32 v[190:191], v[190:191], v[198:199]
	v_cmp_lt_u32_e32 vcc, 4, v173
	s_and_b64 exec, exec, vcc
	v_lshlrev_b32_e32 v198, 16, v60
	v_and_b32_e32 v199, 0xffff0000, v60
	v_lshlrev_b32_e32 v196, 16, v61
	v_and_b32_e32 v197, 0xffff0000, v61
	v_lshlrev_b32_e32 v194, 16, v62
	v_and_b32_e32 v195, 0xffff0000, v62
	v_lshlrev_b32_e32 v192, 16, v63
	v_and_b32_e32 v193, 0xffff0000, v63
	v_pk_add_f32 v[184:185], v[184:185], v[192:193]
	v_pk_add_f32 v[186:187], v[186:187], v[194:195]
	v_pk_add_f32 v[188:189], v[188:189], v[196:197]
	v_pk_add_f32 v[190:191], v[190:191], v[198:199]
	v_cmp_lt_u32_e32 vcc, 5, v173
	s_and_b64 exec, exec, vcc
	v_lshlrev_b32_e32 v198, 16, v64
	v_and_b32_e32 v199, 0xffff0000, v64
	v_lshlrev_b32_e32 v196, 16, v65
	v_and_b32_e32 v197, 0xffff0000, v65
	v_lshlrev_b32_e32 v194, 16, v66
	v_and_b32_e32 v195, 0xffff0000, v66
	v_lshlrev_b32_e32 v192, 16, v67
	v_and_b32_e32 v193, 0xffff0000, v67
	v_pk_add_f32 v[184:185], v[184:185], v[192:193]
	v_pk_add_f32 v[186:187], v[186:187], v[194:195]
	v_pk_add_f32 v[188:189], v[188:189], v[196:197]
	v_pk_add_f32 v[190:191], v[190:191], v[198:199]
	v_cmp_lt_u32_e32 vcc, 6, v173
	s_and_b64 exec, exec, vcc
	v_lshlrev_b32_e32 v198, 16, v68
	v_and_b32_e32 v199, 0xffff0000, v68
	v_lshlrev_b32_e32 v196, 16, v69
	v_and_b32_e32 v197, 0xffff0000, v69
	v_lshlrev_b32_e32 v194, 16, v70
	v_and_b32_e32 v195, 0xffff0000, v70
	v_lshlrev_b32_e32 v192, 16, v71
	v_and_b32_e32 v193, 0xffff0000, v71
	v_pk_add_f32 v[184:185], v[184:185], v[192:193]
	v_pk_add_f32 v[186:187], v[186:187], v[194:195]
	v_pk_add_f32 v[188:189], v[188:189], v[196:197]
	v_pk_add_f32 v[190:191], v[190:191], v[198:199]
	v_cmp_lt_u32_e32 vcc, 7, v173
	s_and_b64 exec, exec, vcc
	v_lshlrev_b32_e32 v198, 16, v72
	v_and_b32_e32 v199, 0xffff0000, v72
	v_lshlrev_b32_e32 v196, 16, v73
	v_and_b32_e32 v197, 0xffff0000, v73
	v_lshlrev_b32_e32 v194, 16, v74
	v_and_b32_e32 v195, 0xffff0000, v74
	v_lshlrev_b32_e32 v192, 16, v75
	v_and_b32_e32 v193, 0xffff0000, v75
	v_pk_add_f32 v[184:185], v[184:185], v[192:193]
	v_pk_add_f32 v[186:187], v[186:187], v[194:195]
	v_pk_add_f32 v[188:189], v[188:189], v[196:197]
	v_pk_add_f32 v[190:191], v[190:191], v[198:199]
	v_cmp_lt_u32_e32 vcc, 8, v173
	s_and_b64 exec, exec, vcc
	v_lshlrev_b32_e32 v198, 16, v76
	v_and_b32_e32 v199, 0xffff0000, v76
	v_lshlrev_b32_e32 v196, 16, v77
	v_and_b32_e32 v197, 0xffff0000, v77
	v_lshlrev_b32_e32 v194, 16, v78
	v_and_b32_e32 v195, 0xffff0000, v78
	v_lshlrev_b32_e32 v192, 16, v79
	v_and_b32_e32 v193, 0xffff0000, v79
	v_pk_add_f32 v[184:185], v[184:185], v[192:193]
	v_pk_add_f32 v[186:187], v[186:187], v[194:195]
	v_pk_add_f32 v[188:189], v[188:189], v[196:197]
	v_pk_add_f32 v[190:191], v[190:191], v[198:199]
	v_cmp_lt_u32_e32 vcc, 9, v173
	s_and_b64 exec, exec, vcc
	v_lshlrev_b32_e32 v198, 16, v80
	v_and_b32_e32 v199, 0xffff0000, v80
	v_lshlrev_b32_e32 v196, 16, v81
	v_and_b32_e32 v197, 0xffff0000, v81
	v_lshlrev_b32_e32 v194, 16, v82
	v_and_b32_e32 v195, 0xffff0000, v82
	v_lshlrev_b32_e32 v192, 16, v83
	v_and_b32_e32 v193, 0xffff0000, v83
	v_pk_add_f32 v[184:185], v[184:185], v[192:193]
	v_pk_add_f32 v[186:187], v[186:187], v[194:195]
	v_pk_add_f32 v[188:189], v[188:189], v[196:197]
	v_pk_add_f32 v[190:191], v[190:191], v[198:199]
	v_cmp_lt_u32_e32 vcc, 10, v173
	s_and_b64 exec, exec, vcc
	v_lshlrev_b32_e32 v198, 16, v84
	v_and_b32_e32 v199, 0xffff0000, v84
	v_lshlrev_b32_e32 v196, 16, v85
	v_and_b32_e32 v197, 0xffff0000, v85
	v_lshlrev_b32_e32 v194, 16, v86
	v_and_b32_e32 v195, 0xffff0000, v86
	v_lshlrev_b32_e32 v192, 16, v87
	v_and_b32_e32 v193, 0xffff0000, v87
	v_pk_add_f32 v[184:185], v[184:185], v[192:193]
	v_pk_add_f32 v[186:187], v[186:187], v[194:195]
	v_pk_add_f32 v[188:189], v[188:189], v[196:197]
	v_pk_add_f32 v[190:191], v[190:191], v[198:199]
	v_cmp_lt_u32_e32 vcc, 11, v173
	s_and_b64 exec, exec, vcc
	v_lshlrev_b32_e32 v198, 16, v88
	v_and_b32_e32 v199, 0xffff0000, v88
	v_lshlrev_b32_e32 v196, 16, v89
	v_and_b32_e32 v197, 0xffff0000, v89
	v_lshlrev_b32_e32 v194, 16, v90
	v_and_b32_e32 v195, 0xffff0000, v90
	v_lshlrev_b32_e32 v192, 16, v91
	v_and_b32_e32 v193, 0xffff0000, v91
	v_pk_add_f32 v[184:185], v[184:185], v[192:193]
	v_pk_add_f32 v[186:187], v[186:187], v[194:195]
	v_pk_add_f32 v[188:189], v[188:189], v[196:197]
	v_pk_add_f32 v[190:191], v[190:191], v[198:199]
	v_cmp_lt_u32_e32 vcc, 12, v173
	s_and_b64 exec, exec, vcc
	v_lshlrev_b32_e32 v198, 16, v92
	v_and_b32_e32 v199, 0xffff0000, v92
	v_lshlrev_b32_e32 v196, 16, v93
	v_and_b32_e32 v197, 0xffff0000, v93
	v_lshlrev_b32_e32 v194, 16, v94
	v_and_b32_e32 v195, 0xffff0000, v94
	v_lshlrev_b32_e32 v192, 16, v95
	v_and_b32_e32 v193, 0xffff0000, v95
	v_pk_add_f32 v[184:185], v[184:185], v[192:193]
	v_pk_add_f32 v[186:187], v[186:187], v[194:195]
	v_pk_add_f32 v[188:189], v[188:189], v[196:197]
	v_pk_add_f32 v[190:191], v[190:191], v[198:199]
	v_cmp_lt_u32_e32 vcc, 13, v173
	s_and_b64 exec, exec, vcc
	v_lshlrev_b32_e32 v198, 16, v96
	v_and_b32_e32 v199, 0xffff0000, v96
	v_lshlrev_b32_e32 v196, 16, v97
	v_and_b32_e32 v197, 0xffff0000, v97
	v_lshlrev_b32_e32 v194, 16, v98
	v_and_b32_e32 v195, 0xffff0000, v98
	v_lshlrev_b32_e32 v192, 16, v99
	v_and_b32_e32 v193, 0xffff0000, v99
	v_pk_add_f32 v[184:185], v[184:185], v[192:193]
	v_pk_add_f32 v[186:187], v[186:187], v[194:195]
	v_pk_add_f32 v[188:189], v[188:189], v[196:197]
	v_pk_add_f32 v[190:191], v[190:191], v[198:199]
	v_cmp_lt_u32_e32 vcc, 14, v173
	s_and_b64 exec, exec, vcc
	v_lshlrev_b32_e32 v198, 16, v100
	v_and_b32_e32 v199, 0xffff0000, v100
	v_lshlrev_b32_e32 v196, 16, v101
	v_and_b32_e32 v197, 0xffff0000, v101
	v_lshlrev_b32_e32 v194, 16, v102
	v_and_b32_e32 v195, 0xffff0000, v102
	v_lshlrev_b32_e32 v192, 16, v103
	v_and_b32_e32 v193, 0xffff0000, v103
	v_pk_add_f32 v[184:185], v[184:185], v[192:193]
	v_pk_add_f32 v[186:187], v[186:187], v[194:195]
	v_pk_add_f32 v[188:189], v[188:189], v[196:197]
	v_pk_add_f32 v[190:191], v[190:191], v[198:199]
	v_cmp_lt_u32_e32 vcc, 15, v173
	s_and_b64 exec, exec, vcc
	v_lshlrev_b32_e32 v198, 16, v104
	v_and_b32_e32 v199, 0xffff0000, v104
	v_lshlrev_b32_e32 v196, 16, v105
	v_and_b32_e32 v197, 0xffff0000, v105
	v_lshlrev_b32_e32 v194, 16, v106
	v_and_b32_e32 v195, 0xffff0000, v106
	v_lshlrev_b32_e32 v192, 16, v107
	v_and_b32_e32 v193, 0xffff0000, v107
	v_pk_add_f32 v[184:185], v[184:185], v[192:193]
	v_pk_add_f32 v[186:187], v[186:187], v[194:195]
	v_pk_add_f32 v[188:189], v[188:189], v[196:197]
	v_pk_add_f32 v[190:191], v[190:191], v[198:199]
	s_mov_b64 exec, s[26:27]
	v_pk_fma_f32 v[184:185], v[184:185], v[174:175], v[176:177] op_sel_hi:[1,0,1] neg_lo:[0,0,1] neg_hi:[0,0,1]
	v_pk_fma_f32 v[186:187], v[186:187], v[174:175], v[178:179] op_sel_hi:[1,0,1] neg_lo:[0,0,1] neg_hi:[0,0,1]
	v_pk_fma_f32 v[188:189], v[188:189], v[174:175], v[180:181] op_sel_hi:[1,0,1] neg_lo:[0,0,1] neg_hi:[0,0,1]
	v_pk_fma_f32 v[190:191], v[190:191], v[174:175], v[182:183] op_sel_hi:[1,0,1] neg_lo:[0,0,1] neg_hi:[0,0,1]
	v_cvt_pk_bf16_f32 v200, v190, v191
	v_cvt_pk_bf16_f32 v201, v188, v189
	v_cvt_pk_bf16_f32 v202, v186, v187
	v_cvt_pk_bf16_f32 v203, v184, v185
	s_lshl_b32 s21, s22, 10
	s_add_u32 s24, s88, s21
	s_addc_u32 s25, s89, 0
	global_store_dwordx4 v175, v[200:203], s[24:25]
	s_add_i32 s22, s22, 0x800
	s_add_i32 s20, s20, 0x800
	s_mov_b32 s21, s20
	s_max_i32 s21, s21, 0
	s_mul_i32 s21, s21, 0x1200
	s_add_u32 s24, s90, s21
	s_addc_u32 s25, s91, 0
	global_load_dwordx4 v[44:47], v172, s[24:25]
	s_sub_i32 s21, s20, 1
	s_max_i32 s21, s21, 0
	s_mul_i32 s21, s21, 0x1200
	s_add_u32 s24, s90, s21
	s_addc_u32 s25, s91, 0
	global_load_dwordx4 v[48:51], v172, s[24:25]
	s_sub_i32 s21, s20, 2
	s_max_i32 s21, s21, 0
	s_mul_i32 s21, s21, 0x1200
	s_add_u32 s24, s90, s21
	s_addc_u32 s25, s91, 0
	global_load_dwordx4 v[52:55], v172, s[24:25]
	s_sub_i32 s21, s20, 3
	s_max_i32 s21, s21, 0
	s_mul_i32 s21, s21, 0x1200
	s_add_u32 s24, s90, s21
	s_addc_u32 s25, s91, 0
	global_load_dwordx4 v[56:59], v172, s[24:25]
	s_sub_i32 s21, s20, 4
	s_max_i32 s21, s21, 0
	s_mul_i32 s21, s21, 0x1200
	s_add_u32 s24, s90, s21
	s_addc_u32 s25, s91, 0
	global_load_dwordx4 v[60:63], v172, s[24:25]
	s_sub_i32 s21, s20, 5
	s_max_i32 s21, s21, 0
	s_mul_i32 s21, s21, 0x1200
	s_add_u32 s24, s90, s21
	s_addc_u32 s25, s91, 0
	global_load_dwordx4 v[64:67], v172, s[24:25]
	s_sub_i32 s21, s20, 6
	s_max_i32 s21, s21, 0
	s_mul_i32 s21, s21, 0x1200
	s_add_u32 s24, s90, s21
	s_addc_u32 s25, s91, 0
	global_load_dwordx4 v[68:71], v172, s[24:25]
	s_sub_i32 s21, s20, 7
	s_max_i32 s21, s21, 0
	s_mul_i32 s21, s21, 0x1200
	s_add_u32 s24, s90, s21
	s_addc_u32 s25, s91, 0
	global_load_dwordx4 v[72:75], v172, s[24:25]
	s_sub_i32 s21, s20, 8
	s_max_i32 s21, s21, 0
	s_mul_i32 s21, s21, 0x1200
	s_add_u32 s24, s90, s21
	s_addc_u32 s25, s91, 0
	global_load_dwordx4 v[76:79], v172, s[24:25]
	s_sub_i32 s21, s20, 9
	s_max_i32 s21, s21, 0
	s_mul_i32 s21, s21, 0x1200
	s_add_u32 s24, s90, s21
	s_addc_u32 s25, s91, 0
	global_load_dwordx4 v[80:83], v172, s[24:25]
	s_sub_i32 s21, s20, 10
	s_max_i32 s21, s21, 0
	s_mul_i32 s21, s21, 0x1200
	s_add_u32 s24, s90, s21
	s_addc_u32 s25, s91, 0
	global_load_dwordx4 v[84:87], v172, s[24:25]
	s_sub_i32 s21, s20, 11
	s_max_i32 s21, s21, 0
	s_mul_i32 s21, s21, 0x1200
	s_add_u32 s24, s90, s21
	s_addc_u32 s25, s91, 0
	global_load_dwordx4 v[88:91], v172, s[24:25]
	s_sub_i32 s21, s20, 12
	s_max_i32 s21, s21, 0
	s_mul_i32 s21, s21, 0x1200
	s_add_u32 s24, s90, s21
	s_addc_u32 s25, s91, 0
	global_load_dwordx4 v[92:95], v172, s[24:25]
	s_sub_i32 s21, s20, 13
	s_max_i32 s21, s21, 0
	s_mul_i32 s21, s21, 0x1200
	s_add_u32 s24, s90, s21
	s_addc_u32 s25, s91, 0
	global_load_dwordx4 v[96:99], v172, s[24:25]
	s_sub_i32 s21, s20, 14
	s_max_i32 s21, s21, 0
	s_mul_i32 s21, s21, 0x1200
	s_add_u32 s24, s90, s21
	s_addc_u32 s25, s91, 0
	global_load_dwordx4 v[100:103], v172, s[24:25]
	s_sub_i32 s21, s20, 15
	s_max_i32 s21, s21, 0
	s_mul_i32 s21, s21, 0x1200
	s_add_u32 s24, s90, s21
	s_addc_u32 s25, s91, 0
	global_load_dwordx4 v[104:107], v172, s[24:25]
	s_waitcnt vmcnt(17)
	v_lshlrev_b32_e32 v182, 16, v108
	v_and_b32_e32 v183, 0xffff0000, v108
	v_lshlrev_b32_e32 v180, 16, v109
	v_and_b32_e32 v181, 0xffff0000, v109
	v_lshlrev_b32_e32 v178, 16, v110
	v_and_b32_e32 v179, 0xffff0000, v110
	v_lshlrev_b32_e32 v176, 16, v111
	v_and_b32_e32 v177, 0xffff0000, v111
	v_mov_b32_e32 v184, v176
	v_mov_b32_e32 v185, v177
	v_mov_b32_e32 v186, v178
	v_mov_b32_e32 v187, v179
	v_mov_b32_e32 v188, v180
	v_mov_b32_e32 v189, v181
	v_mov_b32_e32 v190, v182
	v_mov_b32_e32 v191, v183
	s_mov_b64 s[26:27], exec
	v_cmp_lt_u32_e32 vcc, 1, v173
	s_and_b64 exec, exec, vcc
	v_lshlrev_b32_e32 v198, 16, v112
	v_and_b32_e32 v199, 0xffff0000, v112
	v_lshlrev_b32_e32 v196, 16, v113
	v_and_b32_e32 v197, 0xffff0000, v113
	v_lshlrev_b32_e32 v194, 16, v114
	v_and_b32_e32 v195, 0xffff0000, v114
	v_lshlrev_b32_e32 v192, 16, v115
	v_and_b32_e32 v193, 0xffff0000, v115
	v_pk_add_f32 v[184:185], v[184:185], v[192:193]
	v_pk_add_f32 v[186:187], v[186:187], v[194:195]
	v_pk_add_f32 v[188:189], v[188:189], v[196:197]
	v_pk_add_f32 v[190:191], v[190:191], v[198:199]
	v_cmp_lt_u32_e32 vcc, 2, v173
	s_and_b64 exec, exec, vcc
	v_lshlrev_b32_e32 v198, 16, v116
	v_and_b32_e32 v199, 0xffff0000, v116
	v_lshlrev_b32_e32 v196, 16, v117
	v_and_b32_e32 v197, 0xffff0000, v117
	v_lshlrev_b32_e32 v194, 16, v118
	v_and_b32_e32 v195, 0xffff0000, v118
	v_lshlrev_b32_e32 v192, 16, v119
	v_and_b32_e32 v193, 0xffff0000, v119
	v_pk_add_f32 v[184:185], v[184:185], v[192:193]
	v_pk_add_f32 v[186:187], v[186:187], v[194:195]
	v_pk_add_f32 v[188:189], v[188:189], v[196:197]
	v_pk_add_f32 v[190:191], v[190:191], v[198:199]
	v_cmp_lt_u32_e32 vcc, 3, v173
	s_and_b64 exec, exec, vcc
	v_lshlrev_b32_e32 v198, 16, v120
	v_and_b32_e32 v199, 0xffff0000, v120
	v_lshlrev_b32_e32 v196, 16, v121
	v_and_b32_e32 v197, 0xffff0000, v121
	v_lshlrev_b32_e32 v194, 16, v122
	v_and_b32_e32 v195, 0xffff0000, v122
	v_lshlrev_b32_e32 v192, 16, v123
	v_and_b32_e32 v193, 0xffff0000, v123
	v_pk_add_f32 v[184:185], v[184:185], v[192:193]
	v_pk_add_f32 v[186:187], v[186:187], v[194:195]
	v_pk_add_f32 v[188:189], v[188:189], v[196:197]
	v_pk_add_f32 v[190:191], v[190:191], v[198:199]
	v_cmp_lt_u32_e32 vcc, 4, v173
	s_and_b64 exec, exec, vcc
	v_lshlrev_b32_e32 v198, 16, v124
	v_and_b32_e32 v199, 0xffff0000, v124
	v_lshlrev_b32_e32 v196, 16, v125
	v_and_b32_e32 v197, 0xffff0000, v125
	v_lshlrev_b32_e32 v194, 16, v126
	v_and_b32_e32 v195, 0xffff0000, v126
	v_lshlrev_b32_e32 v192, 16, v127
	v_and_b32_e32 v193, 0xffff0000, v127
	v_pk_add_f32 v[184:185], v[184:185], v[192:193]
	v_pk_add_f32 v[186:187], v[186:187], v[194:195]
	v_pk_add_f32 v[188:189], v[188:189], v[196:197]
	v_pk_add_f32 v[190:191], v[190:191], v[198:199]
	v_cmp_lt_u32_e32 vcc, 5, v173
	s_and_b64 exec, exec, vcc
	v_lshlrev_b32_e32 v198, 16, v128
	v_and_b32_e32 v199, 0xffff0000, v128
	v_lshlrev_b32_e32 v196, 16, v129
	v_and_b32_e32 v197, 0xffff0000, v129
	v_lshlrev_b32_e32 v194, 16, v130
	v_and_b32_e32 v195, 0xffff0000, v130
	v_lshlrev_b32_e32 v192, 16, v131
	v_and_b32_e32 v193, 0xffff0000, v131
	v_pk_add_f32 v[184:185], v[184:185], v[192:193]
	v_pk_add_f32 v[186:187], v[186:187], v[194:195]
	v_pk_add_f32 v[188:189], v[188:189], v[196:197]
	v_pk_add_f32 v[190:191], v[190:191], v[198:199]
	v_cmp_lt_u32_e32 vcc, 6, v173
	s_and_b64 exec, exec, vcc
	v_lshlrev_b32_e32 v198, 16, v132
	v_and_b32_e32 v199, 0xffff0000, v132
	v_lshlrev_b32_e32 v196, 16, v133
	v_and_b32_e32 v197, 0xffff0000, v133
	v_lshlrev_b32_e32 v194, 16, v134
	v_and_b32_e32 v195, 0xffff0000, v134
	v_lshlrev_b32_e32 v192, 16, v135
	v_and_b32_e32 v193, 0xffff0000, v135
	v_pk_add_f32 v[184:185], v[184:185], v[192:193]
	v_pk_add_f32 v[186:187], v[186:187], v[194:195]
	v_pk_add_f32 v[188:189], v[188:189], v[196:197]
	v_pk_add_f32 v[190:191], v[190:191], v[198:199]
	v_cmp_lt_u32_e32 vcc, 7, v173
	s_and_b64 exec, exec, vcc
	v_lshlrev_b32_e32 v198, 16, v136
	v_and_b32_e32 v199, 0xffff0000, v136
	v_lshlrev_b32_e32 v196, 16, v137
	v_and_b32_e32 v197, 0xffff0000, v137
	v_lshlrev_b32_e32 v194, 16, v138
	v_and_b32_e32 v195, 0xffff0000, v138
	v_lshlrev_b32_e32 v192, 16, v139
	v_and_b32_e32 v193, 0xffff0000, v139
	v_pk_add_f32 v[184:185], v[184:185], v[192:193]
	v_pk_add_f32 v[186:187], v[186:187], v[194:195]
	v_pk_add_f32 v[188:189], v[188:189], v[196:197]
	v_pk_add_f32 v[190:191], v[190:191], v[198:199]
	v_cmp_lt_u32_e32 vcc, 8, v173
	s_and_b64 exec, exec, vcc
	v_lshlrev_b32_e32 v198, 16, v140
	v_and_b32_e32 v199, 0xffff0000, v140
	v_lshlrev_b32_e32 v196, 16, v141
	v_and_b32_e32 v197, 0xffff0000, v141
	v_lshlrev_b32_e32 v194, 16, v142
	v_and_b32_e32 v195, 0xffff0000, v142
	v_lshlrev_b32_e32 v192, 16, v143
	v_and_b32_e32 v193, 0xffff0000, v143
	v_pk_add_f32 v[184:185], v[184:185], v[192:193]
	v_pk_add_f32 v[186:187], v[186:187], v[194:195]
	v_pk_add_f32 v[188:189], v[188:189], v[196:197]
	v_pk_add_f32 v[190:191], v[190:191], v[198:199]
	v_cmp_lt_u32_e32 vcc, 9, v173
	s_and_b64 exec, exec, vcc
	v_lshlrev_b32_e32 v198, 16, v144
	v_and_b32_e32 v199, 0xffff0000, v144
	v_lshlrev_b32_e32 v196, 16, v145
	v_and_b32_e32 v197, 0xffff0000, v145
	v_lshlrev_b32_e32 v194, 16, v146
	v_and_b32_e32 v195, 0xffff0000, v146
	v_lshlrev_b32_e32 v192, 16, v147
	v_and_b32_e32 v193, 0xffff0000, v147
	v_pk_add_f32 v[184:185], v[184:185], v[192:193]
	v_pk_add_f32 v[186:187], v[186:187], v[194:195]
	v_pk_add_f32 v[188:189], v[188:189], v[196:197]
	v_pk_add_f32 v[190:191], v[190:191], v[198:199]
	v_cmp_lt_u32_e32 vcc, 10, v173
	s_and_b64 exec, exec, vcc
	v_lshlrev_b32_e32 v198, 16, v148
	v_and_b32_e32 v199, 0xffff0000, v148
	v_lshlrev_b32_e32 v196, 16, v149
	v_and_b32_e32 v197, 0xffff0000, v149
	v_lshlrev_b32_e32 v194, 16, v150
	v_and_b32_e32 v195, 0xffff0000, v150
	v_lshlrev_b32_e32 v192, 16, v151
	v_and_b32_e32 v193, 0xffff0000, v151
	v_pk_add_f32 v[184:185], v[184:185], v[192:193]
	v_pk_add_f32 v[186:187], v[186:187], v[194:195]
	v_pk_add_f32 v[188:189], v[188:189], v[196:197]
	v_pk_add_f32 v[190:191], v[190:191], v[198:199]
	v_cmp_lt_u32_e32 vcc, 11, v173
	s_and_b64 exec, exec, vcc
	v_lshlrev_b32_e32 v198, 16, v152
	v_and_b32_e32 v199, 0xffff0000, v152
	v_lshlrev_b32_e32 v196, 16, v153
	v_and_b32_e32 v197, 0xffff0000, v153
	v_lshlrev_b32_e32 v194, 16, v154
	v_and_b32_e32 v195, 0xffff0000, v154
	v_lshlrev_b32_e32 v192, 16, v155
	v_and_b32_e32 v193, 0xffff0000, v155
	v_pk_add_f32 v[184:185], v[184:185], v[192:193]
	v_pk_add_f32 v[186:187], v[186:187], v[194:195]
	v_pk_add_f32 v[188:189], v[188:189], v[196:197]
	v_pk_add_f32 v[190:191], v[190:191], v[198:199]
	v_cmp_lt_u32_e32 vcc, 12, v173
	s_and_b64 exec, exec, vcc
	v_lshlrev_b32_e32 v198, 16, v156
	v_and_b32_e32 v199, 0xffff0000, v156
	v_lshlrev_b32_e32 v196, 16, v157
	v_and_b32_e32 v197, 0xffff0000, v157
	v_lshlrev_b32_e32 v194, 16, v158
	v_and_b32_e32 v195, 0xffff0000, v158
	v_lshlrev_b32_e32 v192, 16, v159
	v_and_b32_e32 v193, 0xffff0000, v159
	v_pk_add_f32 v[184:185], v[184:185], v[192:193]
	v_pk_add_f32 v[186:187], v[186:187], v[194:195]
	v_pk_add_f32 v[188:189], v[188:189], v[196:197]
	v_pk_add_f32 v[190:191], v[190:191], v[198:199]
	v_cmp_lt_u32_e32 vcc, 13, v173
	s_and_b64 exec, exec, vcc
	v_lshlrev_b32_e32 v198, 16, v160
	v_and_b32_e32 v199, 0xffff0000, v160
	v_lshlrev_b32_e32 v196, 16, v161
	v_and_b32_e32 v197, 0xffff0000, v161
	v_lshlrev_b32_e32 v194, 16, v162
	v_and_b32_e32 v195, 0xffff0000, v162
	v_lshlrev_b32_e32 v192, 16, v163
	v_and_b32_e32 v193, 0xffff0000, v163
	v_pk_add_f32 v[184:185], v[184:185], v[192:193]
	v_pk_add_f32 v[186:187], v[186:187], v[194:195]
	v_pk_add_f32 v[188:189], v[188:189], v[196:197]
	v_pk_add_f32 v[190:191], v[190:191], v[198:199]
	v_cmp_lt_u32_e32 vcc, 14, v173
	s_and_b64 exec, exec, vcc
	v_lshlrev_b32_e32 v198, 16, v164
	v_and_b32_e32 v199, 0xffff0000, v164
	v_lshlrev_b32_e32 v196, 16, v165
	v_and_b32_e32 v197, 0xffff0000, v165
	v_lshlrev_b32_e32 v194, 16, v166
	v_and_b32_e32 v195, 0xffff0000, v166
	v_lshlrev_b32_e32 v192, 16, v167
	v_and_b32_e32 v193, 0xffff0000, v167
	v_pk_add_f32 v[184:185], v[184:185], v[192:193]
	v_pk_add_f32 v[186:187], v[186:187], v[194:195]
	v_pk_add_f32 v[188:189], v[188:189], v[196:197]
	v_pk_add_f32 v[190:191], v[190:191], v[198:199]
	v_cmp_lt_u32_e32 vcc, 15, v173
	s_and_b64 exec, exec, vcc
	v_lshlrev_b32_e32 v198, 16, v168
	v_and_b32_e32 v199, 0xffff0000, v168
	v_lshlrev_b32_e32 v196, 16, v169
	v_and_b32_e32 v197, 0xffff0000, v169
	v_lshlrev_b32_e32 v194, 16, v170
	v_and_b32_e32 v195, 0xffff0000, v170
	v_lshlrev_b32_e32 v192, 16, v171
	v_and_b32_e32 v193, 0xffff0000, v171
	v_pk_add_f32 v[184:185], v[184:185], v[192:193]
	v_pk_add_f32 v[186:187], v[186:187], v[194:195]
	v_pk_add_f32 v[188:189], v[188:189], v[196:197]
	v_pk_add_f32 v[190:191], v[190:191], v[198:199]
	s_mov_b64 exec, s[26:27]
	v_pk_fma_f32 v[184:185], v[184:185], v[174:175], v[176:177] op_sel_hi:[1,0,1] neg_lo:[0,0,1] neg_hi:[0,0,1]
	v_pk_fma_f32 v[186:187], v[186:187], v[174:175], v[178:179] op_sel_hi:[1,0,1] neg_lo:[0,0,1] neg_hi:[0,0,1]
	v_pk_fma_f32 v[188:189], v[188:189], v[174:175], v[180:181] op_sel_hi:[1,0,1] neg_lo:[0,0,1] neg_hi:[0,0,1]
	v_pk_fma_f32 v[190:191], v[190:191], v[174:175], v[182:183] op_sel_hi:[1,0,1] neg_lo:[0,0,1] neg_hi:[0,0,1]
	v_cvt_pk_bf16_f32 v200, v190, v191
	v_cvt_pk_bf16_f32 v201, v188, v189
	v_cvt_pk_bf16_f32 v202, v186, v187
	v_cvt_pk_bf16_f32 v203, v184, v185
	s_lshl_b32 s21, s22, 10
	s_add_u32 s24, s88, s21
	s_addc_u32 s25, s89, 0
	global_store_dwordx4 v175, v[200:203], s[24:25]
	s_add_i32 s22, s22, 0x800
	s_add_i32 s20, s20, 0x800
	s_mov_b32 s21, s20
	s_max_i32 s21, s21, 0
	s_mul_i32 s21, s21, 0x1200
	s_add_u32 s24, s90, s21
	s_addc_u32 s25, s91, 0
	global_load_dwordx4 v[108:111], v172, s[24:25]
	s_sub_i32 s21, s20, 1
	s_max_i32 s21, s21, 0
	s_mul_i32 s21, s21, 0x1200
	s_add_u32 s24, s90, s21
	s_addc_u32 s25, s91, 0
	global_load_dwordx4 v[112:115], v172, s[24:25]
	s_sub_i32 s21, s20, 2
	s_max_i32 s21, s21, 0
	s_mul_i32 s21, s21, 0x1200
	s_add_u32 s24, s90, s21
	s_addc_u32 s25, s91, 0
	global_load_dwordx4 v[116:119], v172, s[24:25]
	s_sub_i32 s21, s20, 3
	s_max_i32 s21, s21, 0
	s_mul_i32 s21, s21, 0x1200
	s_add_u32 s24, s90, s21
	s_addc_u32 s25, s91, 0
	global_load_dwordx4 v[120:123], v172, s[24:25]
	s_sub_i32 s21, s20, 4
	s_max_i32 s21, s21, 0
	s_mul_i32 s21, s21, 0x1200
	s_add_u32 s24, s90, s21
	s_addc_u32 s25, s91, 0
	global_load_dwordx4 v[124:127], v172, s[24:25]
	s_sub_i32 s21, s20, 5
	s_max_i32 s21, s21, 0
	s_mul_i32 s21, s21, 0x1200
	s_add_u32 s24, s90, s21
	s_addc_u32 s25, s91, 0
	global_load_dwordx4 v[128:131], v172, s[24:25]
	s_sub_i32 s21, s20, 6
	s_max_i32 s21, s21, 0
	s_mul_i32 s21, s21, 0x1200
	s_add_u32 s24, s90, s21
	s_addc_u32 s25, s91, 0
	global_load_dwordx4 v[132:135], v172, s[24:25]
	s_sub_i32 s21, s20, 7
	s_max_i32 s21, s21, 0
	s_mul_i32 s21, s21, 0x1200
	s_add_u32 s24, s90, s21
	s_addc_u32 s25, s91, 0
	global_load_dwordx4 v[136:139], v172, s[24:25]
	s_sub_i32 s21, s20, 8
	s_max_i32 s21, s21, 0
	s_mul_i32 s21, s21, 0x1200
	s_add_u32 s24, s90, s21
	s_addc_u32 s25, s91, 0
	global_load_dwordx4 v[140:143], v172, s[24:25]
	s_sub_i32 s21, s20, 9
	s_max_i32 s21, s21, 0
	s_mul_i32 s21, s21, 0x1200
	s_add_u32 s24, s90, s21
	s_addc_u32 s25, s91, 0
	global_load_dwordx4 v[144:147], v172, s[24:25]
	s_sub_i32 s21, s20, 10
	s_max_i32 s21, s21, 0
	s_mul_i32 s21, s21, 0x1200
	s_add_u32 s24, s90, s21
	s_addc_u32 s25, s91, 0
	global_load_dwordx4 v[148:151], v172, s[24:25]
	s_sub_i32 s21, s20, 11
	s_max_i32 s21, s21, 0
	s_mul_i32 s21, s21, 0x1200
	s_add_u32 s24, s90, s21
	s_addc_u32 s25, s91, 0
	global_load_dwordx4 v[152:155], v172, s[24:25]
	s_sub_i32 s21, s20, 12
	s_max_i32 s21, s21, 0
	s_mul_i32 s21, s21, 0x1200
	s_add_u32 s24, s90, s21
	s_addc_u32 s25, s91, 0
	global_load_dwordx4 v[156:159], v172, s[24:25]
	s_sub_i32 s21, s20, 13
	s_max_i32 s21, s21, 0
	s_mul_i32 s21, s21, 0x1200
	s_add_u32 s24, s90, s21
	s_addc_u32 s25, s91, 0
	global_load_dwordx4 v[160:163], v172, s[24:25]
	s_sub_i32 s21, s20, 14
	s_max_i32 s21, s21, 0
	s_mul_i32 s21, s21, 0x1200
	s_add_u32 s24, s90, s21
	s_addc_u32 s25, s91, 0
	global_load_dwordx4 v[164:167], v172, s[24:25]
	s_sub_i32 s21, s20, 15
	s_max_i32 s21, s21, 0
	s_mul_i32 s21, s21, 0x1200
	s_add_u32 s24, s90, s21
	s_addc_u32 s25, s91, 0
	global_load_dwordx4 v[168:171], v172, s[24:25]
	s_waitcnt vmcnt(17)
	v_lshlrev_b32_e32 v182, 16, v44
	v_and_b32_e32 v183, 0xffff0000, v44
	v_lshlrev_b32_e32 v180, 16, v45
	v_and_b32_e32 v181, 0xffff0000, v45
	v_lshlrev_b32_e32 v178, 16, v46
	v_and_b32_e32 v179, 0xffff0000, v46
	v_lshlrev_b32_e32 v176, 16, v47
	v_and_b32_e32 v177, 0xffff0000, v47
	v_mov_b32_e32 v184, v176
	v_mov_b32_e32 v185, v177
	v_mov_b32_e32 v186, v178
	v_mov_b32_e32 v187, v179
	v_mov_b32_e32 v188, v180
	v_mov_b32_e32 v189, v181
	v_mov_b32_e32 v190, v182
	v_mov_b32_e32 v191, v183
	s_mov_b64 s[26:27], exec
	v_cmp_lt_u32_e32 vcc, 1, v173
	s_and_b64 exec, exec, vcc
	v_lshlrev_b32_e32 v198, 16, v48
	v_and_b32_e32 v199, 0xffff0000, v48
	v_lshlrev_b32_e32 v196, 16, v49
	v_and_b32_e32 v197, 0xffff0000, v49
	v_lshlrev_b32_e32 v194, 16, v50
	v_and_b32_e32 v195, 0xffff0000, v50
	v_lshlrev_b32_e32 v192, 16, v51
	v_and_b32_e32 v193, 0xffff0000, v51
	v_pk_add_f32 v[184:185], v[184:185], v[192:193]
	v_pk_add_f32 v[186:187], v[186:187], v[194:195]
	v_pk_add_f32 v[188:189], v[188:189], v[196:197]
	v_pk_add_f32 v[190:191], v[190:191], v[198:199]
	v_cmp_lt_u32_e32 vcc, 2, v173
	s_and_b64 exec, exec, vcc
	v_lshlrev_b32_e32 v198, 16, v52
	v_and_b32_e32 v199, 0xffff0000, v52
	v_lshlrev_b32_e32 v196, 16, v53
	v_and_b32_e32 v197, 0xffff0000, v53
	v_lshlrev_b32_e32 v194, 16, v54
	v_and_b32_e32 v195, 0xffff0000, v54
	v_lshlrev_b32_e32 v192, 16, v55
	v_and_b32_e32 v193, 0xffff0000, v55
	v_pk_add_f32 v[184:185], v[184:185], v[192:193]
	v_pk_add_f32 v[186:187], v[186:187], v[194:195]
	v_pk_add_f32 v[188:189], v[188:189], v[196:197]
	v_pk_add_f32 v[190:191], v[190:191], v[198:199]
	v_cmp_lt_u32_e32 vcc, 3, v173
	s_and_b64 exec, exec, vcc
	v_lshlrev_b32_e32 v198, 16, v56
	v_and_b32_e32 v199, 0xffff0000, v56
	v_lshlrev_b32_e32 v196, 16, v57
	v_and_b32_e32 v197, 0xffff0000, v57
	v_lshlrev_b32_e32 v194, 16, v58
	v_and_b32_e32 v195, 0xffff0000, v58
	v_lshlrev_b32_e32 v192, 16, v59
	v_and_b32_e32 v193, 0xffff0000, v59
	v_pk_add_f32 v[184:185], v[184:185], v[192:193]
	v_pk_add_f32 v[186:187], v[186:187], v[194:195]
	v_pk_add_f32 v[188:189], v[188:189], v[196:197]
	v_pk_add_f32 v[190:191], v[190:191], v[198:199]
	v_cmp_lt_u32_e32 vcc, 4, v173
	s_and_b64 exec, exec, vcc
	v_lshlrev_b32_e32 v198, 16, v60
	v_and_b32_e32 v199, 0xffff0000, v60
	v_lshlrev_b32_e32 v196, 16, v61
	v_and_b32_e32 v197, 0xffff0000, v61
	v_lshlrev_b32_e32 v194, 16, v62
	v_and_b32_e32 v195, 0xffff0000, v62
	v_lshlrev_b32_e32 v192, 16, v63
	v_and_b32_e32 v193, 0xffff0000, v63
	v_pk_add_f32 v[184:185], v[184:185], v[192:193]
	v_pk_add_f32 v[186:187], v[186:187], v[194:195]
	v_pk_add_f32 v[188:189], v[188:189], v[196:197]
	v_pk_add_f32 v[190:191], v[190:191], v[198:199]
	v_cmp_lt_u32_e32 vcc, 5, v173
	s_and_b64 exec, exec, vcc
	v_lshlrev_b32_e32 v198, 16, v64
	v_and_b32_e32 v199, 0xffff0000, v64
	v_lshlrev_b32_e32 v196, 16, v65
	v_and_b32_e32 v197, 0xffff0000, v65
	v_lshlrev_b32_e32 v194, 16, v66
	v_and_b32_e32 v195, 0xffff0000, v66
	v_lshlrev_b32_e32 v192, 16, v67
	v_and_b32_e32 v193, 0xffff0000, v67
	v_pk_add_f32 v[184:185], v[184:185], v[192:193]
	v_pk_add_f32 v[186:187], v[186:187], v[194:195]
	v_pk_add_f32 v[188:189], v[188:189], v[196:197]
	v_pk_add_f32 v[190:191], v[190:191], v[198:199]
	v_cmp_lt_u32_e32 vcc, 6, v173
	s_and_b64 exec, exec, vcc
	v_lshlrev_b32_e32 v198, 16, v68
	v_and_b32_e32 v199, 0xffff0000, v68
	v_lshlrev_b32_e32 v196, 16, v69
	v_and_b32_e32 v197, 0xffff0000, v69
	v_lshlrev_b32_e32 v194, 16, v70
	v_and_b32_e32 v195, 0xffff0000, v70
	v_lshlrev_b32_e32 v192, 16, v71
	v_and_b32_e32 v193, 0xffff0000, v71
	v_pk_add_f32 v[184:185], v[184:185], v[192:193]
	v_pk_add_f32 v[186:187], v[186:187], v[194:195]
	v_pk_add_f32 v[188:189], v[188:189], v[196:197]
	v_pk_add_f32 v[190:191], v[190:191], v[198:199]
	v_cmp_lt_u32_e32 vcc, 7, v173
	s_and_b64 exec, exec, vcc
	v_lshlrev_b32_e32 v198, 16, v72
	v_and_b32_e32 v199, 0xffff0000, v72
	v_lshlrev_b32_e32 v196, 16, v73
	v_and_b32_e32 v197, 0xffff0000, v73
	v_lshlrev_b32_e32 v194, 16, v74
	v_and_b32_e32 v195, 0xffff0000, v74
	v_lshlrev_b32_e32 v192, 16, v75
	v_and_b32_e32 v193, 0xffff0000, v75
	v_pk_add_f32 v[184:185], v[184:185], v[192:193]
	v_pk_add_f32 v[186:187], v[186:187], v[194:195]
	v_pk_add_f32 v[188:189], v[188:189], v[196:197]
	v_pk_add_f32 v[190:191], v[190:191], v[198:199]
	v_cmp_lt_u32_e32 vcc, 8, v173
	s_and_b64 exec, exec, vcc
	v_lshlrev_b32_e32 v198, 16, v76
	v_and_b32_e32 v199, 0xffff0000, v76
	v_lshlrev_b32_e32 v196, 16, v77
	v_and_b32_e32 v197, 0xffff0000, v77
	v_lshlrev_b32_e32 v194, 16, v78
	v_and_b32_e32 v195, 0xffff0000, v78
	v_lshlrev_b32_e32 v192, 16, v79
	v_and_b32_e32 v193, 0xffff0000, v79
	v_pk_add_f32 v[184:185], v[184:185], v[192:193]
	v_pk_add_f32 v[186:187], v[186:187], v[194:195]
	v_pk_add_f32 v[188:189], v[188:189], v[196:197]
	v_pk_add_f32 v[190:191], v[190:191], v[198:199]
	v_cmp_lt_u32_e32 vcc, 9, v173
	s_and_b64 exec, exec, vcc
	v_lshlrev_b32_e32 v198, 16, v80
	v_and_b32_e32 v199, 0xffff0000, v80
	v_lshlrev_b32_e32 v196, 16, v81
	v_and_b32_e32 v197, 0xffff0000, v81
	v_lshlrev_b32_e32 v194, 16, v82
	v_and_b32_e32 v195, 0xffff0000, v82
	v_lshlrev_b32_e32 v192, 16, v83
	v_and_b32_e32 v193, 0xffff0000, v83
	v_pk_add_f32 v[184:185], v[184:185], v[192:193]
	v_pk_add_f32 v[186:187], v[186:187], v[194:195]
	v_pk_add_f32 v[188:189], v[188:189], v[196:197]
	v_pk_add_f32 v[190:191], v[190:191], v[198:199]
	v_cmp_lt_u32_e32 vcc, 10, v173
	s_and_b64 exec, exec, vcc
	v_lshlrev_b32_e32 v198, 16, v84
	v_and_b32_e32 v199, 0xffff0000, v84
	v_lshlrev_b32_e32 v196, 16, v85
	v_and_b32_e32 v197, 0xffff0000, v85
	v_lshlrev_b32_e32 v194, 16, v86
	v_and_b32_e32 v195, 0xffff0000, v86
	v_lshlrev_b32_e32 v192, 16, v87
	v_and_b32_e32 v193, 0xffff0000, v87
	v_pk_add_f32 v[184:185], v[184:185], v[192:193]
	v_pk_add_f32 v[186:187], v[186:187], v[194:195]
	v_pk_add_f32 v[188:189], v[188:189], v[196:197]
	v_pk_add_f32 v[190:191], v[190:191], v[198:199]
	v_cmp_lt_u32_e32 vcc, 11, v173
	s_and_b64 exec, exec, vcc
	v_lshlrev_b32_e32 v198, 16, v88
	v_and_b32_e32 v199, 0xffff0000, v88
	v_lshlrev_b32_e32 v196, 16, v89
	v_and_b32_e32 v197, 0xffff0000, v89
	v_lshlrev_b32_e32 v194, 16, v90
	v_and_b32_e32 v195, 0xffff0000, v90
	v_lshlrev_b32_e32 v192, 16, v91
	v_and_b32_e32 v193, 0xffff0000, v91
	v_pk_add_f32 v[184:185], v[184:185], v[192:193]
	v_pk_add_f32 v[186:187], v[186:187], v[194:195]
	v_pk_add_f32 v[188:189], v[188:189], v[196:197]
	v_pk_add_f32 v[190:191], v[190:191], v[198:199]
	v_cmp_lt_u32_e32 vcc, 12, v173
	s_and_b64 exec, exec, vcc
	v_lshlrev_b32_e32 v198, 16, v92
	v_and_b32_e32 v199, 0xffff0000, v92
	v_lshlrev_b32_e32 v196, 16, v93
	v_and_b32_e32 v197, 0xffff0000, v93
	v_lshlrev_b32_e32 v194, 16, v94
	v_and_b32_e32 v195, 0xffff0000, v94
	v_lshlrev_b32_e32 v192, 16, v95
	v_and_b32_e32 v193, 0xffff0000, v95
	v_pk_add_f32 v[184:185], v[184:185], v[192:193]
	v_pk_add_f32 v[186:187], v[186:187], v[194:195]
	v_pk_add_f32 v[188:189], v[188:189], v[196:197]
	v_pk_add_f32 v[190:191], v[190:191], v[198:199]
	v_cmp_lt_u32_e32 vcc, 13, v173
	s_and_b64 exec, exec, vcc
	v_lshlrev_b32_e32 v198, 16, v96
	v_and_b32_e32 v199, 0xffff0000, v96
	v_lshlrev_b32_e32 v196, 16, v97
	v_and_b32_e32 v197, 0xffff0000, v97
	v_lshlrev_b32_e32 v194, 16, v98
	v_and_b32_e32 v195, 0xffff0000, v98
	v_lshlrev_b32_e32 v192, 16, v99
	v_and_b32_e32 v193, 0xffff0000, v99
	v_pk_add_f32 v[184:185], v[184:185], v[192:193]
	v_pk_add_f32 v[186:187], v[186:187], v[194:195]
	v_pk_add_f32 v[188:189], v[188:189], v[196:197]
	v_pk_add_f32 v[190:191], v[190:191], v[198:199]
	v_cmp_lt_u32_e32 vcc, 14, v173
	s_and_b64 exec, exec, vcc
	v_lshlrev_b32_e32 v198, 16, v100
	v_and_b32_e32 v199, 0xffff0000, v100
	v_lshlrev_b32_e32 v196, 16, v101
	v_and_b32_e32 v197, 0xffff0000, v101
	v_lshlrev_b32_e32 v194, 16, v102
	v_and_b32_e32 v195, 0xffff0000, v102
	v_lshlrev_b32_e32 v192, 16, v103
	v_and_b32_e32 v193, 0xffff0000, v103
	v_pk_add_f32 v[184:185], v[184:185], v[192:193]
	v_pk_add_f32 v[186:187], v[186:187], v[194:195]
	v_pk_add_f32 v[188:189], v[188:189], v[196:197]
	v_pk_add_f32 v[190:191], v[190:191], v[198:199]
	v_cmp_lt_u32_e32 vcc, 15, v173
	s_and_b64 exec, exec, vcc
	v_lshlrev_b32_e32 v198, 16, v104
	v_and_b32_e32 v199, 0xffff0000, v104
	v_lshlrev_b32_e32 v196, 16, v105
	v_and_b32_e32 v197, 0xffff0000, v105
	v_lshlrev_b32_e32 v194, 16, v106
	v_and_b32_e32 v195, 0xffff0000, v106
	v_lshlrev_b32_e32 v192, 16, v107
	v_and_b32_e32 v193, 0xffff0000, v107
	v_pk_add_f32 v[184:185], v[184:185], v[192:193]
	v_pk_add_f32 v[186:187], v[186:187], v[194:195]
	v_pk_add_f32 v[188:189], v[188:189], v[196:197]
	v_pk_add_f32 v[190:191], v[190:191], v[198:199]
	s_mov_b64 exec, s[26:27]
	v_pk_fma_f32 v[184:185], v[184:185], v[174:175], v[176:177] op_sel_hi:[1,0,1] neg_lo:[0,0,1] neg_hi:[0,0,1]
	v_pk_fma_f32 v[186:187], v[186:187], v[174:175], v[178:179] op_sel_hi:[1,0,1] neg_lo:[0,0,1] neg_hi:[0,0,1]
	v_pk_fma_f32 v[188:189], v[188:189], v[174:175], v[180:181] op_sel_hi:[1,0,1] neg_lo:[0,0,1] neg_hi:[0,0,1]
	v_pk_fma_f32 v[190:191], v[190:191], v[174:175], v[182:183] op_sel_hi:[1,0,1] neg_lo:[0,0,1] neg_hi:[0,0,1]
	v_cvt_pk_bf16_f32 v200, v190, v191
	v_cvt_pk_bf16_f32 v201, v188, v189
	v_cvt_pk_bf16_f32 v202, v186, v187
	v_cvt_pk_bf16_f32 v203, v184, v185
	s_lshl_b32 s21, s22, 10
	s_add_u32 s24, s88, s21
	s_addc_u32 s25, s89, 0
	global_store_dwordx4 v175, v[200:203], s[24:25]
	s_add_i32 s22, s22, 0x800
	s_waitcnt vmcnt(1)
	v_lshlrev_b32_e32 v182, 16, v108
	v_and_b32_e32 v183, 0xffff0000, v108
	v_lshlrev_b32_e32 v180, 16, v109
	v_and_b32_e32 v181, 0xffff0000, v109
	v_lshlrev_b32_e32 v178, 16, v110
	v_and_b32_e32 v179, 0xffff0000, v110
	v_lshlrev_b32_e32 v176, 16, v111
	v_and_b32_e32 v177, 0xffff0000, v111
	v_mov_b32_e32 v184, v176
	v_mov_b32_e32 v185, v177
	v_mov_b32_e32 v186, v178
	v_mov_b32_e32 v187, v179
	v_mov_b32_e32 v188, v180
	v_mov_b32_e32 v189, v181
	v_mov_b32_e32 v190, v182
	v_mov_b32_e32 v191, v183
	s_mov_b64 s[26:27], exec
	v_cmp_lt_u32_e32 vcc, 1, v173
	s_and_b64 exec, exec, vcc
	v_lshlrev_b32_e32 v198, 16, v112
	v_and_b32_e32 v199, 0xffff0000, v112
	v_lshlrev_b32_e32 v196, 16, v113
	v_and_b32_e32 v197, 0xffff0000, v113
	v_lshlrev_b32_e32 v194, 16, v114
	v_and_b32_e32 v195, 0xffff0000, v114
	v_lshlrev_b32_e32 v192, 16, v115
	v_and_b32_e32 v193, 0xffff0000, v115
	v_pk_add_f32 v[184:185], v[184:185], v[192:193]
	v_pk_add_f32 v[186:187], v[186:187], v[194:195]
	v_pk_add_f32 v[188:189], v[188:189], v[196:197]
	v_pk_add_f32 v[190:191], v[190:191], v[198:199]
	v_cmp_lt_u32_e32 vcc, 2, v173
	s_and_b64 exec, exec, vcc
	v_lshlrev_b32_e32 v198, 16, v116
	v_and_b32_e32 v199, 0xffff0000, v116
	v_lshlrev_b32_e32 v196, 16, v117
	v_and_b32_e32 v197, 0xffff0000, v117
	v_lshlrev_b32_e32 v194, 16, v118
	v_and_b32_e32 v195, 0xffff0000, v118
	v_lshlrev_b32_e32 v192, 16, v119
	v_and_b32_e32 v193, 0xffff0000, v119
	v_pk_add_f32 v[184:185], v[184:185], v[192:193]
	v_pk_add_f32 v[186:187], v[186:187], v[194:195]
	v_pk_add_f32 v[188:189], v[188:189], v[196:197]
	v_pk_add_f32 v[190:191], v[190:191], v[198:199]
	v_cmp_lt_u32_e32 vcc, 3, v173
	s_and_b64 exec, exec, vcc
	v_lshlrev_b32_e32 v198, 16, v120
	v_and_b32_e32 v199, 0xffff0000, v120
	v_lshlrev_b32_e32 v196, 16, v121
	v_and_b32_e32 v197, 0xffff0000, v121
	v_lshlrev_b32_e32 v194, 16, v122
	v_and_b32_e32 v195, 0xffff0000, v122
	v_lshlrev_b32_e32 v192, 16, v123
	v_and_b32_e32 v193, 0xffff0000, v123
	v_pk_add_f32 v[184:185], v[184:185], v[192:193]
	v_pk_add_f32 v[186:187], v[186:187], v[194:195]
	v_pk_add_f32 v[188:189], v[188:189], v[196:197]
	v_pk_add_f32 v[190:191], v[190:191], v[198:199]
	v_cmp_lt_u32_e32 vcc, 4, v173
	s_and_b64 exec, exec, vcc
	v_lshlrev_b32_e32 v198, 16, v124
	v_and_b32_e32 v199, 0xffff0000, v124
	v_lshlrev_b32_e32 v196, 16, v125
	v_and_b32_e32 v197, 0xffff0000, v125
	v_lshlrev_b32_e32 v194, 16, v126
	v_and_b32_e32 v195, 0xffff0000, v126
	v_lshlrev_b32_e32 v192, 16, v127
	v_and_b32_e32 v193, 0xffff0000, v127
	v_pk_add_f32 v[184:185], v[184:185], v[192:193]
	v_pk_add_f32 v[186:187], v[186:187], v[194:195]
	v_pk_add_f32 v[188:189], v[188:189], v[196:197]
	v_pk_add_f32 v[190:191], v[190:191], v[198:199]
	v_cmp_lt_u32_e32 vcc, 5, v173
	s_and_b64 exec, exec, vcc
	v_lshlrev_b32_e32 v198, 16, v128
	v_and_b32_e32 v199, 0xffff0000, v128
	v_lshlrev_b32_e32 v196, 16, v129
	v_and_b32_e32 v197, 0xffff0000, v129
	v_lshlrev_b32_e32 v194, 16, v130
	v_and_b32_e32 v195, 0xffff0000, v130
	v_lshlrev_b32_e32 v192, 16, v131
	v_and_b32_e32 v193, 0xffff0000, v131
	v_pk_add_f32 v[184:185], v[184:185], v[192:193]
	v_pk_add_f32 v[186:187], v[186:187], v[194:195]
	v_pk_add_f32 v[188:189], v[188:189], v[196:197]
	v_pk_add_f32 v[190:191], v[190:191], v[198:199]
	v_cmp_lt_u32_e32 vcc, 6, v173
	s_and_b64 exec, exec, vcc
	v_lshlrev_b32_e32 v198, 16, v132
	v_and_b32_e32 v199, 0xffff0000, v132
	v_lshlrev_b32_e32 v196, 16, v133
	v_and_b32_e32 v197, 0xffff0000, v133
	v_lshlrev_b32_e32 v194, 16, v134
	v_and_b32_e32 v195, 0xffff0000, v134
	v_lshlrev_b32_e32 v192, 16, v135
	v_and_b32_e32 v193, 0xffff0000, v135
	v_pk_add_f32 v[184:185], v[184:185], v[192:193]
	v_pk_add_f32 v[186:187], v[186:187], v[194:195]
	v_pk_add_f32 v[188:189], v[188:189], v[196:197]
	v_pk_add_f32 v[190:191], v[190:191], v[198:199]
	v_cmp_lt_u32_e32 vcc, 7, v173
	s_and_b64 exec, exec, vcc
	v_lshlrev_b32_e32 v198, 16, v136
	v_and_b32_e32 v199, 0xffff0000, v136
	v_lshlrev_b32_e32 v196, 16, v137
	v_and_b32_e32 v197, 0xffff0000, v137
	v_lshlrev_b32_e32 v194, 16, v138
	v_and_b32_e32 v195, 0xffff0000, v138
	v_lshlrev_b32_e32 v192, 16, v139
	v_and_b32_e32 v193, 0xffff0000, v139
	v_pk_add_f32 v[184:185], v[184:185], v[192:193]
	v_pk_add_f32 v[186:187], v[186:187], v[194:195]
	v_pk_add_f32 v[188:189], v[188:189], v[196:197]
	v_pk_add_f32 v[190:191], v[190:191], v[198:199]
	v_cmp_lt_u32_e32 vcc, 8, v173
	s_and_b64 exec, exec, vcc
	v_lshlrev_b32_e32 v198, 16, v140
	v_and_b32_e32 v199, 0xffff0000, v140
	v_lshlrev_b32_e32 v196, 16, v141
	v_and_b32_e32 v197, 0xffff0000, v141
	v_lshlrev_b32_e32 v194, 16, v142
	v_and_b32_e32 v195, 0xffff0000, v142
	v_lshlrev_b32_e32 v192, 16, v143
	v_and_b32_e32 v193, 0xffff0000, v143
	v_pk_add_f32 v[184:185], v[184:185], v[192:193]
	v_pk_add_f32 v[186:187], v[186:187], v[194:195]
	v_pk_add_f32 v[188:189], v[188:189], v[196:197]
	v_pk_add_f32 v[190:191], v[190:191], v[198:199]
	v_cmp_lt_u32_e32 vcc, 9, v173
	s_and_b64 exec, exec, vcc
	v_lshlrev_b32_e32 v198, 16, v144
	v_and_b32_e32 v199, 0xffff0000, v144
	v_lshlrev_b32_e32 v196, 16, v145
	v_and_b32_e32 v197, 0xffff0000, v145
	v_lshlrev_b32_e32 v194, 16, v146
	v_and_b32_e32 v195, 0xffff0000, v146
	v_lshlrev_b32_e32 v192, 16, v147
	v_and_b32_e32 v193, 0xffff0000, v147
	v_pk_add_f32 v[184:185], v[184:185], v[192:193]
	v_pk_add_f32 v[186:187], v[186:187], v[194:195]
	v_pk_add_f32 v[188:189], v[188:189], v[196:197]
	v_pk_add_f32 v[190:191], v[190:191], v[198:199]
	v_cmp_lt_u32_e32 vcc, 10, v173
	s_and_b64 exec, exec, vcc
	v_lshlrev_b32_e32 v198, 16, v148
	v_and_b32_e32 v199, 0xffff0000, v148
	v_lshlrev_b32_e32 v196, 16, v149
	v_and_b32_e32 v197, 0xffff0000, v149
	v_lshlrev_b32_e32 v194, 16, v150
	v_and_b32_e32 v195, 0xffff0000, v150
	v_lshlrev_b32_e32 v192, 16, v151
	v_and_b32_e32 v193, 0xffff0000, v151
	v_pk_add_f32 v[184:185], v[184:185], v[192:193]
	v_pk_add_f32 v[186:187], v[186:187], v[194:195]
	v_pk_add_f32 v[188:189], v[188:189], v[196:197]
	v_pk_add_f32 v[190:191], v[190:191], v[198:199]
	v_cmp_lt_u32_e32 vcc, 11, v173
	s_and_b64 exec, exec, vcc
	v_lshlrev_b32_e32 v198, 16, v152
	v_and_b32_e32 v199, 0xffff0000, v152
	v_lshlrev_b32_e32 v196, 16, v153
	v_and_b32_e32 v197, 0xffff0000, v153
	v_lshlrev_b32_e32 v194, 16, v154
	v_and_b32_e32 v195, 0xffff0000, v154
	v_lshlrev_b32_e32 v192, 16, v155
	v_and_b32_e32 v193, 0xffff0000, v155
	v_pk_add_f32 v[184:185], v[184:185], v[192:193]
	v_pk_add_f32 v[186:187], v[186:187], v[194:195]
	v_pk_add_f32 v[188:189], v[188:189], v[196:197]
	v_pk_add_f32 v[190:191], v[190:191], v[198:199]
	v_cmp_lt_u32_e32 vcc, 12, v173
	s_and_b64 exec, exec, vcc
	v_lshlrev_b32_e32 v198, 16, v156
	v_and_b32_e32 v199, 0xffff0000, v156
	v_lshlrev_b32_e32 v196, 16, v157
	v_and_b32_e32 v197, 0xffff0000, v157
	v_lshlrev_b32_e32 v194, 16, v158
	v_and_b32_e32 v195, 0xffff0000, v158
	v_lshlrev_b32_e32 v192, 16, v159
	v_and_b32_e32 v193, 0xffff0000, v159
	v_pk_add_f32 v[184:185], v[184:185], v[192:193]
	v_pk_add_f32 v[186:187], v[186:187], v[194:195]
	v_pk_add_f32 v[188:189], v[188:189], v[196:197]
	v_pk_add_f32 v[190:191], v[190:191], v[198:199]
	v_cmp_lt_u32_e32 vcc, 13, v173
	s_and_b64 exec, exec, vcc
	v_lshlrev_b32_e32 v198, 16, v160
	v_and_b32_e32 v199, 0xffff0000, v160
	v_lshlrev_b32_e32 v196, 16, v161
	v_and_b32_e32 v197, 0xffff0000, v161
	v_lshlrev_b32_e32 v194, 16, v162
	v_and_b32_e32 v195, 0xffff0000, v162
	v_lshlrev_b32_e32 v192, 16, v163
	v_and_b32_e32 v193, 0xffff0000, v163
	v_pk_add_f32 v[184:185], v[184:185], v[192:193]
	v_pk_add_f32 v[186:187], v[186:187], v[194:195]
	v_pk_add_f32 v[188:189], v[188:189], v[196:197]
	v_pk_add_f32 v[190:191], v[190:191], v[198:199]
	v_cmp_lt_u32_e32 vcc, 14, v173
	s_and_b64 exec, exec, vcc
	v_lshlrev_b32_e32 v198, 16, v164
	v_and_b32_e32 v199, 0xffff0000, v164
	v_lshlrev_b32_e32 v196, 16, v165
	v_and_b32_e32 v197, 0xffff0000, v165
	v_lshlrev_b32_e32 v194, 16, v166
	v_and_b32_e32 v195, 0xffff0000, v166
	v_lshlrev_b32_e32 v192, 16, v167
	v_and_b32_e32 v193, 0xffff0000, v167
	v_pk_add_f32 v[184:185], v[184:185], v[192:193]
	v_pk_add_f32 v[186:187], v[186:187], v[194:195]
	v_pk_add_f32 v[188:189], v[188:189], v[196:197]
	v_pk_add_f32 v[190:191], v[190:191], v[198:199]
	v_cmp_lt_u32_e32 vcc, 15, v173
	s_and_b64 exec, exec, vcc
	v_lshlrev_b32_e32 v198, 16, v168
	v_and_b32_e32 v199, 0xffff0000, v168
	v_lshlrev_b32_e32 v196, 16, v169
	v_and_b32_e32 v197, 0xffff0000, v169
	v_lshlrev_b32_e32 v194, 16, v170
	v_and_b32_e32 v195, 0xffff0000, v170
	v_lshlrev_b32_e32 v192, 16, v171
	v_and_b32_e32 v193, 0xffff0000, v171
	v_pk_add_f32 v[184:185], v[184:185], v[192:193]
	v_pk_add_f32 v[186:187], v[186:187], v[194:195]
	v_pk_add_f32 v[188:189], v[188:189], v[196:197]
	v_pk_add_f32 v[190:191], v[190:191], v[198:199]
	s_mov_b64 exec, s[26:27]
	v_pk_fma_f32 v[184:185], v[184:185], v[174:175], v[176:177] op_sel_hi:[1,0,1] neg_lo:[0,0,1] neg_hi:[0,0,1]
	v_pk_fma_f32 v[186:187], v[186:187], v[174:175], v[178:179] op_sel_hi:[1,0,1] neg_lo:[0,0,1] neg_hi:[0,0,1]
	v_pk_fma_f32 v[188:189], v[188:189], v[174:175], v[180:181] op_sel_hi:[1,0,1] neg_lo:[0,0,1] neg_hi:[0,0,1]
	v_pk_fma_f32 v[190:191], v[190:191], v[174:175], v[182:183] op_sel_hi:[1,0,1] neg_lo:[0,0,1] neg_hi:[0,0,1]
	v_cvt_pk_bf16_f32 v200, v190, v191
	v_cvt_pk_bf16_f32 v201, v188, v189
	v_cvt_pk_bf16_f32 v202, v186, v187
	v_cvt_pk_bf16_f32 v203, v184, v185
	s_lshl_b32 s21, s22, 10
	s_add_u32 s24, s88, s21
	s_addc_u32 s25, s89, 0
	global_store_dwordx4 v175, v[200:203], s[24:25]
	s_add_i32 s22, s22, 0x800
	s_cmpk_lt_i32 s2, 0x180
	s_cbranch_scc1 .LBB0_271
	s_sub_i32 s28, 0x1ff, s2
	s_lshl_b32 s20, s28, 2
	s_add_i32 s20, s20, s23
	s_add_i32 s20, s20, 0x4000
	s_mul_i32 s28, s28, 15
	s_add_i32 s28, s28, s23
	s_add_i32 s28, s28, 15
	v_add_u32_e32 v173, 0xfffff200, v172
	v_lshlrev_b32_e32 v173, 1, v173
	v_and_b32_e32 v174, 63, v218
	v_lshrrev_b32_e32 v174, 4, v174
	s_mul_i32 s21, s20, 0x1200
	s_add_u32 s24, s90, s21
	s_addc_u32 s25, s91, 0
	global_load_dwordx4 v[164:167], v172, s[24:25]
	s_cmp_ge_i32 s23, 1
	s_cbranch_scc1 .Lps_lz1
	s_sub_i32 s21, s28, 1
	s_lshl_b32 s21, s21, 11
	s_add_u32 s24, s72, s21
	s_addc_u32 s25, s73, 0
	global_load_dwordx4 v[44:47], v173, s[24:25]
	global_load_dwordx4 v[48:51], v173, s[24:25] offset:16
	s_branch .Lps_ld1
.Lps_lz1:
	s_sub_i32 s21, s20, 1
	s_mul_i32 s21, s21, 0x1200
	s_add_u32 s24, s90, s21
	s_addc_u32 s25, s91, 0
	global_load_dwordx4 v[44:47], v172, s[24:25]
.Lps_ld1:
	s_cmp_ge_i32 s23, 2
	s_cbranch_scc1 .Lps_lz2
	s_sub_i32 s21, s28, 2
	s_lshl_b32 s21, s21, 11
	s_add_u32 s24, s72, s21
	s_addc_u32 s25, s73, 0
	global_load_dwordx4 v[52:55], v173, s[24:25]
	global_load_dwordx4 v[56:59], v173, s[24:25] offset:16
	s_branch .Lps_ld2
.Lps_lz2:
	s_sub_i32 s21, s20, 2
	s_mul_i32 s21, s21, 0x1200
	s_add_u32 s24, s90, s21
	s_addc_u32 s25, s91, 0
	global_load_dwordx4 v[52:55], v172, s[24:25]
.Lps_ld2:
	s_cmp_ge_i32 s23, 3
	s_cbranch_scc1 .Lps_lz3
	s_sub_i32 s21, s28, 3
	s_lshl_b32 s21, s21, 11
	s_add_u32 s24, s72, s21
	s_addc_u32 s25, s73, 0
	global_load_dwordx4 v[60:63], v173, s[24:25]
	global_load_dwordx4 v[64:67], v173, s[24:25] offset:16
	s_branch .Lps_ld3
.Lps_lz3:
	s_sub_i32 s21, s20, 3
	s_mul_i32 s21, s21, 0x1200
	s_add_u32 s24, s90, s21
	s_addc_u32 s25, s91, 0
	global_load_dwordx4 v[60:63], v172, s[24:25]
.Lps_ld3:
	s_sub_i32 s21, s28, 4
	s_lshl_b32 s21, s21, 11
	s_add_u32 s24, s72, s21
	s_addc_u32 s25, s73, 0
	global_load_dwordx4 v[68:71], v173, s[24:25]
	global_load_dwordx4 v[72:75], v173, s[24:25] offset:16
	s_sub_i32 s21, s28, 5
	s_lshl_b32 s21, s21, 11
	s_add_u32 s24, s72, s21
	s_addc_u32 s25, s73, 0
	global_load_dwordx4 v[76:79], v173, s[24:25]
	global_load_dwordx4 v[80:83], v173, s[24:25] offset:16
	s_sub_i32 s21, s28, 6
	s_lshl_b32 s21, s21, 11
	s_add_u32 s24, s72, s21
	s_addc_u32 s25, s73, 0
	global_load_dwordx4 v[84:87], v173, s[24:25]
	global_load_dwordx4 v[88:91], v173, s[24:25] offset:16
	s_sub_i32 s21, s28, 7
	s_lshl_b32 s21, s21, 11
	s_add_u32 s24, s72, s21
	s_addc_u32 s25, s73, 0
	global_load_dwordx4 v[92:95], v173, s[24:25]
	global_load_dwordx4 v[96:99], v173, s[24:25] offset:16
	s_sub_i32 s21, s28, 8
	s_lshl_b32 s21, s21, 11
	s_add_u32 s24, s72, s21
	s_addc_u32 s25, s73, 0
	global_load_dwordx4 v[100:103], v173, s[24:25]
	global_load_dwordx4 v[104:107], v173, s[24:25] offset:16
	s_sub_i32 s21, s28, 9
	s_lshl_b32 s21, s21, 11
	s_add_u32 s24, s72, s21
	s_addc_u32 s25, s73, 0
	global_load_dwordx4 v[108:111], v173, s[24:25]
	global_load_dwordx4 v[112:115], v173, s[24:25] offset:16
	s_sub_i32 s21, s28, 10
	s_lshl_b32 s21, s21, 11
	s_add_u32 s24, s72, s21
	s_addc_u32 s25, s73, 0
	global_load_dwordx4 v[116:119], v173, s[24:25]
	global_load_dwordx4 v[120:123], v173, s[24:25] offset:16
	s_sub_i32 s21, s28, 11
	s_lshl_b32 s21, s21, 11
	s_add_u32 s24, s72, s21
	s_addc_u32 s25, s73, 0
	global_load_dwordx4 v[124:127], v173, s[24:25]
	global_load_dwordx4 v[128:131], v173, s[24:25] offset:16
	s_sub_i32 s21, s28, 12
	s_lshl_b32 s21, s21, 11
	s_add_u32 s24, s72, s21
	s_addc_u32 s25, s73, 0
	global_load_dwordx4 v[132:135], v173, s[24:25]
	global_load_dwordx4 v[136:139], v173, s[24:25] offset:16
	s_sub_i32 s21, s28, 13
	s_lshl_b32 s21, s21, 11
	s_add_u32 s24, s72, s21
	s_addc_u32 s25, s73, 0
	global_load_dwordx4 v[140:143], v173, s[24:25]
	global_load_dwordx4 v[144:147], v173, s[24:25] offset:16
	s_sub_i32 s21, s28, 14
	s_lshl_b32 s21, s21, 11
	s_add_u32 s24, s72, s21
	s_addc_u32 s25, s73, 0
	global_load_dwordx4 v[148:151], v173, s[24:25]
	global_load_dwordx4 v[152:155], v173, s[24:25] offset:16
	s_sub_i32 s21, s28, 15
	s_lshl_b32 s21, s21, 11
	s_add_u32 s24, s72, s21
	s_addc_u32 s25, s73, 0
	global_load_dwordx4 v[156:159], v173, s[24:25]
	global_load_dwordx4 v[160:163], v173, s[24:25] offset:16
	v_lshlrev_b32_e64 v175, v174, 2
	v_sub_u32_e32 v174, 0x7e, v174
	v_lshlrev_b32_e32 v174, 23, v174
	s_waitcnt vmcnt(0)
	v_lshlrev_b32_e32 v176, 16, v164
	v_and_b32_e32 v177, 0xffff0000, v164
	v_lshlrev_b32_e32 v178, 16, v165
	v_and_b32_e32 v179, 0xffff0000, v165
	v_lshlrev_b32_e32 v180, 16, v166
	v_and_b32_e32 v181, 0xffff0000, v166
	v_lshlrev_b32_e32 v182, 16, v167
	v_and_b32_e32 v183, 0xffff0000, v167
	v_mov_b32_e32 v184, v176
	v_mov_b32_e32 v185, v177
	v_mov_b32_e32 v186, v178
	v_mov_b32_e32 v187, v179
	v_mov_b32_e32 v188, v180
	v_mov_b32_e32 v189, v181
	v_mov_b32_e32 v190, v182
	v_mov_b32_e32 v191, v183
	s_mov_b64 s[26:27], exec
	v_cmp_lt_u32_e32 vcc, 1, v175
	s_and_b64 exec, exec, vcc
	s_cmp_ge_i32 s23, 1
	s_cbranch_scc1 .Lps_az1
	v_pk_add_f32 v[184:185], v[184:185], v[44:45]
	v_pk_add_f32 v[186:187], v[186:187], v[46:47]
	v_pk_add_f32 v[188:189], v[188:189], v[48:49]
	v_pk_add_f32 v[190:191], v[190:191], v[50:51]
	s_branch .Lps_ad1
.Lps_az1:
	v_lshlrev_b32_e32 v192, 16, v44
	v_and_b32_e32 v193, 0xffff0000, v44
	v_lshlrev_b32_e32 v194, 16, v45
	v_and_b32_e32 v195, 0xffff0000, v45
	v_lshlrev_b32_e32 v196, 16, v46
	v_and_b32_e32 v197, 0xffff0000, v46
	v_lshlrev_b32_e32 v198, 16, v47
	v_and_b32_e32 v199, 0xffff0000, v47
	v_pk_add_f32 v[184:185], v[184:185], v[192:193]
	v_pk_add_f32 v[186:187], v[186:187], v[194:195]
	v_pk_add_f32 v[188:189], v[188:189], v[196:197]
	v_pk_add_f32 v[190:191], v[190:191], v[198:199]
.Lps_ad1:
	v_cmp_lt_u32_e32 vcc, 2, v175
	s_and_b64 exec, exec, vcc
	s_cmp_ge_i32 s23, 2
	s_cbranch_scc1 .Lps_az2
	v_pk_add_f32 v[184:185], v[184:185], v[52:53]
	v_pk_add_f32 v[186:187], v[186:187], v[54:55]
	v_pk_add_f32 v[188:189], v[188:189], v[56:57]
	v_pk_add_f32 v[190:191], v[190:191], v[58:59]
	s_branch .Lps_ad2
.Lps_az2:
	v_lshlrev_b32_e32 v192, 16, v52
	v_and_b32_e32 v193, 0xffff0000, v52
	v_lshlrev_b32_e32 v194, 16, v53
	v_and_b32_e32 v195, 0xffff0000, v53
	v_lshlrev_b32_e32 v196, 16, v54
	v_and_b32_e32 v197, 0xffff0000, v54
	v_lshlrev_b32_e32 v198, 16, v55
	v_and_b32_e32 v199, 0xffff0000, v55
	v_pk_add_f32 v[184:185], v[184:185], v[192:193]
	v_pk_add_f32 v[186:187], v[186:187], v[194:195]
	v_pk_add_f32 v[188:189], v[188:189], v[196:197]
	v_pk_add_f32 v[190:191], v[190:191], v[198:199]
.Lps_ad2:
	v_cmp_lt_u32_e32 vcc, 3, v175
	s_and_b64 exec, exec, vcc
	s_cmp_ge_i32 s23, 3
	s_cbranch_scc1 .Lps_az3
	v_pk_add_f32 v[184:185], v[184:185], v[60:61]
	v_pk_add_f32 v[186:187], v[186:187], v[62:63]
	v_pk_add_f32 v[188:189], v[188:189], v[64:65]
	v_pk_add_f32 v[190:191], v[190:191], v[66:67]
	s_branch .Lps_ad3
.Lps_az3:
	v_lshlrev_b32_e32 v192, 16, v60
	v_and_b32_e32 v193, 0xffff0000, v60
	v_lshlrev_b32_e32 v194, 16, v61
	v_and_b32_e32 v195, 0xffff0000, v61
	v_lshlrev_b32_e32 v196, 16, v62
	v_and_b32_e32 v197, 0xffff0000, v62
	v_lshlrev_b32_e32 v198, 16, v63
	v_and_b32_e32 v199, 0xffff0000, v63
	v_pk_add_f32 v[184:185], v[184:185], v[192:193]
	v_pk_add_f32 v[186:187], v[186:187], v[194:195]
	v_pk_add_f32 v[188:189], v[188:189], v[196:197]
	v_pk_add_f32 v[190:191], v[190:191], v[198:199]
.Lps_ad3:
	v_cmp_lt_u32_e32 vcc, 4, v175
	s_and_b64 exec, exec, vcc
	v_pk_add_f32 v[184:185], v[184:185], v[68:69]
	v_pk_add_f32 v[186:187], v[186:187], v[70:71]
	v_pk_add_f32 v[188:189], v[188:189], v[72:73]
	v_pk_add_f32 v[190:191], v[190:191], v[74:75]
	v_cmp_lt_u32_e32 vcc, 5, v175
	s_and_b64 exec, exec, vcc
	v_pk_add_f32 v[184:185], v[184:185], v[76:77]
	v_pk_add_f32 v[186:187], v[186:187], v[78:79]
	v_pk_add_f32 v[188:189], v[188:189], v[80:81]
	v_pk_add_f32 v[190:191], v[190:191], v[82:83]
	v_cmp_lt_u32_e32 vcc, 6, v175
	s_and_b64 exec, exec, vcc
	v_pk_add_f32 v[184:185], v[184:185], v[84:85]
	v_pk_add_f32 v[186:187], v[186:187], v[86:87]
	v_pk_add_f32 v[188:189], v[188:189], v[88:89]
	v_pk_add_f32 v[190:191], v[190:191], v[90:91]
	v_cmp_lt_u32_e32 vcc, 7, v175
	s_and_b64 exec, exec, vcc
	v_pk_add_f32 v[184:185], v[184:185], v[92:93]
	v_pk_add_f32 v[186:187], v[186:187], v[94:95]
	v_pk_add_f32 v[188:189], v[188:189], v[96:97]
	v_pk_add_f32 v[190:191], v[190:191], v[98:99]
	v_cmp_lt_u32_e32 vcc, 8, v175
	s_and_b64 exec, exec, vcc
	v_pk_add_f32 v[184:185], v[184:185], v[100:101]
	v_pk_add_f32 v[186:187], v[186:187], v[102:103]
	v_pk_add_f32 v[188:189], v[188:189], v[104:105]
	v_pk_add_f32 v[190:191], v[190:191], v[106:107]
	v_cmp_lt_u32_e32 vcc, 9, v175
	s_and_b64 exec, exec, vcc
	v_pk_add_f32 v[184:185], v[184:185], v[108:109]
	v_pk_add_f32 v[186:187], v[186:187], v[110:111]
	v_pk_add_f32 v[188:189], v[188:189], v[112:113]
	v_pk_add_f32 v[190:191], v[190:191], v[114:115]
	v_cmp_lt_u32_e32 vcc, 10, v175
	s_and_b64 exec, exec, vcc
	v_pk_add_f32 v[184:185], v[184:185], v[116:117]
	v_pk_add_f32 v[186:187], v[186:187], v[118:119]
	v_pk_add_f32 v[188:189], v[188:189], v[120:121]
	v_pk_add_f32 v[190:191], v[190:191], v[122:123]
	v_cmp_lt_u32_e32 vcc, 11, v175
	s_and_b64 exec, exec, vcc
	v_pk_add_f32 v[184:185], v[184:185], v[124:125]
	v_pk_add_f32 v[186:187], v[186:187], v[126:127]
	v_pk_add_f32 v[188:189], v[188:189], v[128:129]
	v_pk_add_f32 v[190:191], v[190:191], v[130:131]
	v_cmp_lt_u32_e32 vcc, 12, v175
	s_and_b64 exec, exec, vcc
	v_pk_add_f32 v[184:185], v[184:185], v[132:133]
	v_pk_add_f32 v[186:187], v[186:187], v[134:135]
	v_pk_add_f32 v[188:189], v[188:189], v[136:137]
	v_pk_add_f32 v[190:191], v[190:191], v[138:139]
	v_cmp_lt_u32_e32 vcc, 13, v175
	s_and_b64 exec, exec, vcc
	v_pk_add_f32 v[184:185], v[184:185], v[140:141]
	v_pk_add_f32 v[186:187], v[186:187], v[142:143]
	v_pk_add_f32 v[188:189], v[188:189], v[144:145]
	v_pk_add_f32 v[190:191], v[190:191], v[146:147]
	v_cmp_lt_u32_e32 vcc, 14, v175
	s_and_b64 exec, exec, vcc
	v_pk_add_f32 v[184:185], v[184:185], v[148:149]
	v_pk_add_f32 v[186:187], v[186:187], v[150:151]
	v_pk_add_f32 v[188:189], v[188:189], v[152:153]
	v_pk_add_f32 v[190:191], v[190:191], v[154:155]
	v_cmp_lt_u32_e32 vcc, 15, v175
	s_and_b64 exec, exec, vcc
	v_pk_add_f32 v[184:185], v[184:185], v[156:157]
	v_pk_add_f32 v[186:187], v[186:187], v[158:159]
	v_pk_add_f32 v[188:189], v[188:189], v[160:161]
	v_pk_add_f32 v[190:191], v[190:191], v[162:163]
	s_mov_b64 exec, s[26:27]
	v_pk_fma_f32 v[184:185], v[184:185], v[174:175], v[176:177] op_sel_hi:[1,0,1] neg_lo:[0,0,1] neg_hi:[0,0,1]
	v_pk_fma_f32 v[186:187], v[186:187], v[174:175], v[178:179] op_sel_hi:[1,0,1] neg_lo:[0,0,1] neg_hi:[0,0,1]
	v_pk_fma_f32 v[188:189], v[188:189], v[174:175], v[180:181] op_sel_hi:[1,0,1] neg_lo:[0,0,1] neg_hi:[0,0,1]
	v_pk_fma_f32 v[190:191], v[190:191], v[174:175], v[182:183] op_sel_hi:[1,0,1] neg_lo:[0,0,1] neg_hi:[0,0,1]
	v_cvt_pk_bf16_f32 v200, v184, v185
	v_cvt_pk_bf16_f32 v201, v186, v187
	v_cvt_pk_bf16_f32 v202, v188, v189
	v_cvt_pk_bf16_f32 v203, v190, v191
	v_and_b32_e32 v173, 63, v218
	v_lshlrev_b32_e32 v173, 4, v173
	s_lshl_b32 s21, s20, 10
	s_add_u32 s24, s88, s21
	s_addc_u32 s25, s89, 0
	global_store_dwordx4 v173, v[200:203], s[24:25]
	s_branch .LBB0_271
